# up-projection GEMM epilogue: conditional row-pair stores merged into global_store_dwordx4 through v_permlane16_swap, lane mask rebuilt from both rows
# speedup vs baseline: 1.0169x; 1.0063x over previous
; DI unsigned pack2(float a, float b) { f2_t v = {a, b}; return __builtin_bit_cast(unsigned, __builtin_convertvector(v, bf2_t)); }
;   DI void operator()(const f32x4 (&acc)[2][2][4][2], const pg8::Unit& u, int wr, int wc, int fr, int fq) const {
;     ...
;           if (q >= 1 && q <= 62 && tok < S)
;             *(uint2*)(act + (size_t)(b * S + tok) * DFF + col) = make_uint2(pack2(r[0], r[1]), pack2(r[2], r[3]));
.LBB0_656:
	s_or_b64 exec, exec, s[16:17]
	v_mov_b32_e32 v244, v2
	v_mov_b32_e32 v245, v3
	s_nop 1
	v_permlane16_swap_b32_e32 v242, v244
	v_permlane16_swap_b32_e32 v243, v245
	s_and_b32 s98, s98, 0xffff
	s_and_b32 s99, s99, 0xffff
	s_and_b32 s100, s100, 0xffff0000
	s_and_b32 s101, s101, 0xffff0000
	s_or_b64 s[98:99], s[98:99], s[100:101]
	s_mov_b64 s[100:101], exec
	s_mov_b64 exec, s[98:99]
	global_store_dwordx4 v[246:247], v[242:245], off offset:32
	s_mov_b64 exec, s[100:101]
	s_and_b64 vcc, exec, s[48:49]
	s_mov_b32 s52, s58
	s_mov_b32 s56, s7
	s_mov_b64 s[16:17], s[62:63]
	s_mov_b64 s[36:37], s[60:61]
	s_cbranch_vccnz .LBB0_715

; DI unsigned pack2(float a, float b) { f2_t v = {a, b}; return __builtin_bit_cast(unsigned, __builtin_convertvector(v, bf2_t)); }
; DI float exp2_hw(float x) { return __builtin_amdgcn_exp2f(x); }
; DI float dpp_ror1(float v)  { return __builtin_bit_cast(float, __builtin_amdgcn_update_dpp(0, __builtin_bit_cast(int, v), 0x121, 0xf, 0xf, false)); }
; DI float dpp_ror15(float v) { return __builtin_bit_cast(float, __builtin_amdgcn_update_dpp(0, __builtin_bit_cast(int, v), 0x12F, 0xf, 0xf, false)); }
;   DI void operator()(const f32x4 (&acc)[2][2][4][2], const pg8::Unit& u, int wr, int wc, int fr, int fq) const {
;     ...
; #pragma unroll
;         for (int m = 0; m < 4; ++m) {
;           const int q = 16 * m + fr, tok = tokb + q;
;           f32x4 r;
; #pragma unroll
;           for (int e = 0; e < 4; ++e) {
;             const float srcm = (fr == 15 && m > 0) ? g[m > 0 ? m - 1 : 0][e] : g[m][e];
;             const float srcp = (fr == 0 && m < 3) ? g[m < 3 ? m + 1 : 3][e] : g[m][e];
;             const float gm = dpp_ror1(srcm), gp = dpp_ror15(srcp);
;             const float cv = bb[e] + w0[e] * gm + w1[e] * g[m][e] + w2[e] * gp;
;             r[e] = cv * __builtin_amdgcn_rcpf(1.f + exp2_hw(-LOG2E * cv)) * acc[ai][1][m][n][e];
;           }
;           if (q >= 1 && q <= 62 && tok < S)
;             *(uint2*)(act + (size_t)(b * S + tok) * DFF + col) = make_uint2(pack2(r[0], r[1]), pack2(r[2], r[3]));
.LBB0_671:
	v_cndmask_b32_e64 v148, v192, v188, s[42:43]
	v_mov_b32_e32 v154, v1
	v_mov_b32_e32 v155, v1
	v_cndmask_b32_e64 v149, v190, v186, s[42:43]
	v_mov_b32_dpp v154, v148 row_ror:15 row_mask:0xf bank_mask:0xf
	v_cndmask_b32_e64 v148, v193, v189, s[42:43]
	v_mov_b32_e32 v150, v1
	s_lshl_b32 s59, s50, 14
	v_mov_b32_e32 v152, v1
	v_mov_b32_e32 v153, v1
	v_mov_b32_dpp v155, v148 row_ror:15 row_mask:0xf bank_mask:0xf
	v_mov_b32_e32 v148, v1
	v_mov_b32_dpp v150, v149 row_ror:15 row_mask:0xf bank_mask:0xf
	v_cndmask_b32_e64 v156, v191, v187, s[42:43]
	v_mov_b32_e32 v149, v1
	v_mov_b32_e32 v151, v1
	v_cmp_gt_i32_e32 vcc, s5, v201
	v_mov_b32_dpp v152, v192 row_ror:1 row_mask:0xf bank_mask:0xf
	v_mov_b32_dpp v153, v193 row_ror:1 row_mask:0xf bank_mask:0xf
	v_mov_b32_dpp v148, v190 row_ror:1 row_mask:0xf bank_mask:0xf
	v_mov_b32_dpp v149, v191 row_ror:1 row_mask:0xf bank_mask:0xf
	v_mov_b32_dpp v151, v156 row_ror:15 row_mask:0xf bank_mask:0xf
	s_and_b64 s[36:37], s[44:45], vcc
	v_add_u32_e32 v156, s59, v201
	s_mov_b64 s[98:99], s[36:37]
	s_and_saveexec_b64 s[50:51], s[36:37]
	s_cbranch_execz .LBB0_673
	s_waitcnt vmcnt(0)
	v_pk_fma_f32 v[152:153], v[128:129], v[152:153], v[140:141]
	v_pk_fma_f32 v[148:149], v[130:131], v[148:149], v[142:143]
	v_pk_fma_f32 v[152:153], v[132:133], v[192:193], v[152:153]
	v_pk_fma_f32 v[148:149], v[134:135], v[190:191], v[148:149]
	v_pk_fma_f32 v[152:153], v[136:137], v[154:155], v[152:153]
	v_pk_fma_f32 v[148:149], v[138:139], v[150:151], v[148:149]
	v_mul_f32_e32 v154, 0xbfb8aa3b, v152
	v_mul_f32_e32 v155, 0xbfb8aa3b, v153
	v_mul_f32_e32 v150, 0xbfb8aa3b, v148
	v_mul_f32_e32 v151, 0xbfb8aa3b, v149
	v_exp_f32_e32 v154, v154
	v_exp_f32_e32 v155, v155
	v_exp_f32_e32 v150, v150
	v_exp_f32_e32 v151, v151
	v_add_f32_e32 v154, 1.0, v154
	v_add_f32_e32 v155, 1.0, v155
	v_add_f32_e32 v150, 1.0, v150
	v_add_f32_e32 v151, 1.0, v151
	v_rcp_f32_e32 v154, v154
	v_rcp_f32_e32 v155, v155
	v_rcp_f32_e32 v150, v150
	v_rcp_f32_e32 v151, v151
	v_pk_mul_f32 v[152:153], v[152:153], v[154:155]
	s_nop 0
	v_pk_mul_f32 v[144:145], v[144:145], v[152:153]
	v_pk_mul_f32 v[148:149], v[148:149], v[150:151]
	v_cvt_pk_bf16_f32 v144, v144, v145
	v_pk_mul_f32 v[146:147], v[146:147], v[148:149]
	s_nop 0
	v_cvt_pk_bf16_f32 v145, v146, v147
	v_mov_b64_e32 v[146:147], s[24:25]
	v_mad_i64_i32 v[146:147], s[52:53], v156, s0, v[146:147]
	v_lshl_add_u64 v[146:147], v[172:173], 1, v[146:147]
.LBB0_673:
	s_or_b64 exec, exec, s[50:51]
	v_mov_b64_e32 v[246:247], s[24:25]
	v_mad_i64_i32 v[246:247], s[100:101], v156, s0, v[246:247]
	v_lshl_add_u64 v[246:247], v[172:173], 1, v[246:247]
	v_bfe_u32 v244, v227, 4, 1
	v_mul_u32_u24_e32 v244, 0x15ff8, v244
	v_mov_b32_e32 v245, 0
	v_lshl_add_u64 v[246:247], v[246:247], 0, v[244:245]
	v_mov_b32_e32 v242, v144
	v_mov_b32_e32 v243, v145
	v_cndmask_b32_e64 v144, v188, v192, s[40:41]
	v_cndmask_b32_e64 v145, v188, v184, s[42:43]
	v_mov_b32_e32 v148, v1
	v_mov_b32_e32 v150, v1
	v_mov_b32_e32 v149, v1
	v_mov_b32_dpp v148, v144 row_ror:1 row_mask:0xf bank_mask:0xf
	v_mov_b32_dpp v150, v145 row_ror:15 row_mask:0xf bank_mask:0xf
	v_cndmask_b32_e64 v144, v189, v193, s[40:41]
	v_cndmask_b32_e64 v145, v189, v185, s[42:43]
	v_mov_b32_e32 v151, v1
	v_mov_b32_dpp v149, v144 row_ror:1 row_mask:0xf bank_mask:0xf
	v_cndmask_b32_e64 v147, v186, v182, s[42:43]
	v_mov_b32_dpp v151, v145 row_ror:15 row_mask:0xf bank_mask:0xf
	v_cndmask_b32_e64 v145, v186, v190, s[40:41]
	v_mov_b32_e32 v144, v1
	v_mov_b32_e32 v146, v1
	v_cndmask_b32_e64 v152, v187, v183, s[42:43]
	v_mov_b32_dpp v144, v145 row_ror:1 row_mask:0xf bank_mask:0xf
	v_mov_b32_dpp v146, v147 row_ror:15 row_mask:0xf bank_mask:0xf
	v_cndmask_b32_e64 v147, v187, v191, s[40:41]
	v_mov_b32_e32 v145, v1
	s_nop 1
	v_mov_b32_dpp v145, v147 row_ror:1 row_mask:0xf bank_mask:0xf
	v_mov_b32_e32 v147, v1
	s_nop 1
	v_mov_b32_dpp v147, v152 row_ror:15 row_mask:0xf bank_mask:0xf
	v_add_u32_e32 v152, s56, v196
	v_cmp_gt_i32_e64 s[50:51], s5, v152
	v_add_u32_e32 v152, s59, v152
	s_mov_b64 s[100:101], s[50:51]
	s_and_saveexec_b64 s[52:53], s[50:51]
	s_cbranch_execz .LBB0_675
	s_waitcnt vmcnt(0)
	v_pk_fma_f32 v[148:149], v[128:129], v[148:149], v[140:141]
	v_pk_fma_f32 v[144:145], v[130:131], v[144:145], v[142:143]
	v_pk_fma_f32 v[148:149], v[132:133], v[188:189], v[148:149]
	v_pk_fma_f32 v[144:145], v[134:135], v[186:187], v[144:145]
	v_pk_fma_f32 v[148:149], v[136:137], v[150:151], v[148:149]
	v_pk_fma_f32 v[144:145], v[138:139], v[146:147], v[144:145]
	v_mul_f32_e32 v150, 0xbfb8aa3b, v148
	v_mul_f32_e32 v151, 0xbfb8aa3b, v149
	v_mul_f32_e32 v146, 0xbfb8aa3b, v144
	v_mul_f32_e32 v147, 0xbfb8aa3b, v145
	v_exp_f32_e32 v150, v150
	v_exp_f32_e32 v151, v151
	v_exp_f32_e32 v146, v146
	v_exp_f32_e32 v147, v147
	v_add_f32_e32 v150, 1.0, v150
	v_add_f32_e32 v151, 1.0, v151
	v_add_f32_e32 v146, 1.0, v146
	v_add_f32_e32 v147, 1.0, v147
	v_rcp_f32_e32 v150, v150
	v_rcp_f32_e32 v151, v151
	v_rcp_f32_e32 v146, v146
	v_rcp_f32_e32 v147, v147
	v_pk_mul_f32 v[148:149], v[148:149], v[150:151]
	s_nop 0
	v_pk_mul_f32 v[124:125], v[124:125], v[148:149]
	v_pk_mul_f32 v[144:145], v[144:145], v[146:147]
	v_cvt_pk_bf16_f32 v124, v124, v125
	v_pk_mul_f32 v[126:127], v[126:127], v[144:145]
	s_nop 0
	v_cvt_pk_bf16_f32 v125, v126, v127
	v_mov_b64_e32 v[126:127], s[24:25]
	v_mad_i64_i32 v[126:127], s[54:55], v152, s0, v[126:127]
	v_lshl_add_u64 v[126:127], v[172:173], 1, v[126:127]
; DI unsigned pack2(float a, float b) { f2_t v = {a, b}; return __builtin_bit_cast(unsigned, __builtin_convertvector(v, bf2_t)); }
; DI float exp2_hw(float x) { return __builtin_amdgcn_exp2f(x); }
; DI float dpp_ror1(float v)  { return __builtin_bit_cast(float, __builtin_amdgcn_update_dpp(0, __builtin_bit_cast(int, v), 0x121, 0xf, 0xf, false)); }
; DI float dpp_ror15(float v) { return __builtin_bit_cast(float, __builtin_amdgcn_update_dpp(0, __builtin_bit_cast(int, v), 0x12F, 0xf, 0xf, false)); }
;   DI void operator()(const f32x4 (&acc)[2][2][4][2], const pg8::Unit& u, int wr, int wc, int fr, int fq) const {
;     ...
; #pragma unroll
;         for (int m = 0; m < 4; ++m) {
;           const int q = 16 * m + fr, tok = tokb + q;
;           f32x4 r;
; #pragma unroll
;           for (int e = 0; e < 4; ++e) {
;             const float srcm = (fr == 15 && m > 0) ? g[m > 0 ? m - 1 : 0][e] : g[m][e];
;             const float srcp = (fr == 0 && m < 3) ? g[m < 3 ? m + 1 : 3][e] : g[m][e];
;             const float gm = dpp_ror1(srcm), gp = dpp_ror15(srcp);
;             const float cv = bb[e] + w0[e] * gm + w1[e] * g[m][e] + w2[e] * gp;
;             r[e] = cv * __builtin_amdgcn_rcpf(1.f + exp2_hw(-LOG2E * cv)) * acc[ai][1][m][n][e];
;           }
;           if (q >= 1 && q <= 62 && tok < S)
;             *(uint2*)(act + (size_t)(b * S + tok) * DFF + col) = make_uint2(pack2(r[0], r[1]), pack2(r[2], r[3]));
.LBB0_675:
	s_or_b64 exec, exec, s[52:53]
	v_mov_b32_e32 v244, v124
	v_mov_b32_e32 v245, v125
	s_nop 1
	v_permlane16_swap_b32_e32 v242, v244
	v_permlane16_swap_b32_e32 v243, v245
	s_and_b32 s98, s98, 0xffff
	s_and_b32 s99, s99, 0xffff
	s_and_b32 s100, s100, 0xffff0000
	s_and_b32 s101, s101, 0xffff0000
	s_or_b64 s[98:99], s[98:99], s[100:101]
	s_mov_b64 s[100:101], exec
	s_mov_b64 exec, s[98:99]
	global_store_dwordx4 v[246:247], v[242:245], off
	s_mov_b64 exec, s[100:101]
	v_cndmask_b32_e64 v124, v184, v188, s[40:41]
	v_cndmask_b32_e64 v125, v184, v180, s[42:43]
	v_mov_b32_e32 v144, v1
	v_mov_b32_e32 v146, v1
	v_mov_b32_e32 v145, v1
	v_mov_b32_dpp v144, v124 row_ror:1 row_mask:0xf bank_mask:0xf
	v_mov_b32_dpp v146, v125 row_ror:15 row_mask:0xf bank_mask:0xf
	v_cndmask_b32_e64 v124, v185, v189, s[40:41]
	v_cndmask_b32_e64 v125, v185, v181, s[42:43]
	v_mov_b32_e32 v147, v1
	v_mov_b32_dpp v145, v124 row_ror:1 row_mask:0xf bank_mask:0xf
	v_cndmask_b32_e64 v127, v182, v178, s[42:43]
	v_mov_b32_dpp v147, v125 row_ror:15 row_mask:0xf bank_mask:0xf
	v_cndmask_b32_e64 v125, v182, v186, s[40:41]
	v_mov_b32_e32 v124, v1
	v_mov_b32_e32 v126, v1
	v_cndmask_b32_e64 v148, v183, v179, s[42:43]
	v_mov_b32_dpp v124, v125 row_ror:1 row_mask:0xf bank_mask:0xf
	v_mov_b32_dpp v126, v127 row_ror:15 row_mask:0xf bank_mask:0xf
	v_cndmask_b32_e64 v127, v183, v187, s[40:41]
	v_mov_b32_e32 v125, v1
	s_nop 1
	v_mov_b32_dpp v125, v127 row_ror:1 row_mask:0xf bank_mask:0xf
	v_mov_b32_e32 v127, v1
	s_nop 1
	v_mov_b32_dpp v127, v148 row_ror:15 row_mask:0xf bank_mask:0xf
	v_add_u32_e32 v148, s56, v197
	v_cmp_gt_i32_e64 s[52:53], s5, v148
	v_add_u32_e32 v148, s59, v148
	s_mov_b64 s[98:99], s[52:53]
	s_and_saveexec_b64 s[54:55], s[52:53]
	s_cbranch_execz .LBB0_677
	s_waitcnt vmcnt(0)
	v_pk_fma_f32 v[144:145], v[128:129], v[144:145], v[140:141]
	v_pk_fma_f32 v[124:125], v[130:131], v[124:125], v[142:143]
	v_pk_fma_f32 v[144:145], v[132:133], v[184:185], v[144:145]
	v_pk_fma_f32 v[124:125], v[134:135], v[182:183], v[124:125]
	v_pk_fma_f32 v[144:145], v[136:137], v[146:147], v[144:145]
	v_pk_fma_f32 v[124:125], v[138:139], v[126:127], v[124:125]
	v_mul_f32_e32 v146, 0xbfb8aa3b, v144
	v_mul_f32_e32 v147, 0xbfb8aa3b, v145
	v_mul_f32_e32 v126, 0xbfb8aa3b, v124
	v_mul_f32_e32 v127, 0xbfb8aa3b, v125
	v_exp_f32_e32 v146, v146
	v_exp_f32_e32 v147, v147
	v_exp_f32_e32 v126, v126
	v_exp_f32_e32 v127, v127
	v_add_f32_e32 v146, 1.0, v146
	v_add_f32_e32 v147, 1.0, v147
	v_add_f32_e32 v126, 1.0, v126
	v_add_f32_e32 v127, 1.0, v127
	v_rcp_f32_e32 v146, v146
	v_rcp_f32_e32 v147, v147
	v_rcp_f32_e32 v126, v126
	v_rcp_f32_e32 v127, v127
	v_pk_mul_f32 v[144:145], v[144:145], v[146:147]
	s_nop 0
	v_pk_mul_f32 v[120:121], v[120:121], v[144:145]
	v_pk_mul_f32 v[124:125], v[124:125], v[126:127]
	v_cvt_pk_bf16_f32 v120, v120, v121
	v_pk_mul_f32 v[122:123], v[122:123], v[124:125]
	s_nop 0
	v_cvt_pk_bf16_f32 v121, v122, v123
	v_mov_b64_e32 v[122:123], s[24:25]
	v_mad_i64_i32 v[122:123], s[64:65], v148, s0, v[122:123]
	v_lshl_add_u64 v[122:123], v[172:173], 1, v[122:123]
; DI unsigned pack2(float a, float b) { f2_t v = {a, b}; return __builtin_bit_cast(unsigned, __builtin_convertvector(v, bf2_t)); }
; DI float exp2_hw(float x) { return __builtin_amdgcn_exp2f(x); }
; DI float dpp_ror1(float v)  { return __builtin_bit_cast(float, __builtin_amdgcn_update_dpp(0, __builtin_bit_cast(int, v), 0x121, 0xf, 0xf, false)); }
; DI float dpp_ror15(float v) { return __builtin_bit_cast(float, __builtin_amdgcn_update_dpp(0, __builtin_bit_cast(int, v), 0x12F, 0xf, 0xf, false)); }
;   DI void operator()(const f32x4 (&acc)[2][2][4][2], const pg8::Unit& u, int wr, int wc, int fr, int fq) const {
;     ...
;         const int tokb = 248 * ti - 1 + 62 * (2 * ai + wr);
;         f32x4 g[4];
;         if (tokb >= 0 && tokb + 63 < S) {
; #pragma unroll
;           for (int m = 0; m < 4; ++m) g[m] = acc[ai][0][m][n];
;         } else {
; #pragma unroll
;           for (int m = 0; m < 4; ++m) {
;             const int tok = tokb + 16 * m + fr;
;             const bool ok = (tok >= 0) && (tok < S);
; #pragma unroll
;             for (int e = 0; e < 4; ++e) g[m][e] = ok ? acc[ai][0][m][n][e] : 0.f;
;           }
;         }
; #pragma unroll
;         for (int m = 0; m < 4; ++m) {
;           const int q = 16 * m + fr, tok = tokb + q;
;           f32x4 r;
; #pragma unroll
;           for (int e = 0; e < 4; ++e) {
;             const float srcm = (fr == 15 && m > 0) ? g[m > 0 ? m - 1 : 0][e] : g[m][e];
;             const float srcp = (fr == 0 && m < 3) ? g[m < 3 ? m + 1 : 3][e] : g[m][e];
;             const float gm = dpp_ror1(srcm), gp = dpp_ror15(srcp);
;             const float cv = bb[e] + w0[e] * gm + w1[e] * g[m][e] + w2[e] * gp;
;             r[e] = cv * __builtin_amdgcn_rcpf(1.f + exp2_hw(-LOG2E * cv)) * acc[ai][1][m][n][e];
;           }
;           if (q >= 1 && q <= 62 && tok < S)
;             *(uint2*)(act + (size_t)(b * S + tok) * DFF + col) = make_uint2(pack2(r[0], r[1]), pack2(r[2], r[3]));
.LBB0_677:
	s_or_b64 exec, exec, s[54:55]
	v_mov_b64_e32 v[246:247], s[24:25]
	v_mad_i64_i32 v[246:247], s[100:101], v148, s0, v[246:247]
	v_lshl_add_u64 v[246:247], v[172:173], 1, v[246:247]
	v_bfe_u32 v244, v227, 4, 1
	v_mul_u32_u24_e32 v244, 0x15ff8, v244
	v_mov_b32_e32 v245, 0
	v_lshl_add_u64 v[246:247], v[246:247], 0, v[244:245]
	v_mov_b32_e32 v242, v120
	v_mov_b32_e32 v243, v121
	v_cndmask_b32_e64 v120, v180, v184, s[40:41]
	v_mov_b32_e32 v124, v1
	v_mov_b32_e32 v125, v1
	v_cndmask_b32_e64 v121, v178, v182, s[40:41]
	v_mov_b32_dpp v124, v120 row_ror:1 row_mask:0xf bank_mask:0xf
	v_cndmask_b32_e64 v120, v181, v185, s[40:41]
	v_cndmask_b32_e64 v123, v179, v183, s[40:41]
	v_add_u32_e32 v144, s56, v198
	v_mov_b32_dpp v125, v120 row_ror:1 row_mask:0xf bank_mask:0xf
	v_mov_b32_e32 v120, v1
	v_mov_b32_e32 v126, v1
	v_mov_b32_e32 v127, v1
	v_mov_b32_dpp v120, v121 row_ror:1 row_mask:0xf bank_mask:0xf
	v_mov_b32_e32 v121, v1
	v_mov_b32_e32 v122, v1
	v_cmp_gt_i32_e32 vcc, s5, v144
	v_mov_b32_dpp v121, v123 row_ror:1 row_mask:0xf bank_mask:0xf
	v_mov_b32_e32 v123, v1
	v_mov_b32_dpp v126, v180 row_ror:15 row_mask:0xf bank_mask:0xf
	v_mov_b32_dpp v127, v181 row_ror:15 row_mask:0xf bank_mask:0xf
	v_mov_b32_dpp v122, v178 row_ror:15 row_mask:0xf bank_mask:0xf
	v_mov_b32_dpp v123, v179 row_ror:15 row_mask:0xf bank_mask:0xf
	s_and_b64 s[64:65], s[46:47], vcc
	v_add_u32_e32 v149, s59, v144
	s_mov_b64 s[100:101], s[64:65]
	s_and_saveexec_b64 s[54:55], s[64:65]
	s_cbranch_execz .LBB0_679
	s_waitcnt vmcnt(0)
	v_pk_fma_f32 v[124:125], v[128:129], v[124:125], v[140:141]
	v_pk_fma_f32 v[120:121], v[130:131], v[120:121], v[142:143]
	v_pk_fma_f32 v[124:125], v[132:133], v[180:181], v[124:125]
	v_pk_fma_f32 v[120:121], v[134:135], v[178:179], v[120:121]
	v_pk_fma_f32 v[124:125], v[136:137], v[126:127], v[124:125]
	v_pk_fma_f32 v[120:121], v[138:139], v[122:123], v[120:121]
	v_mul_f32_e32 v126, 0xbfb8aa3b, v124
	v_mul_f32_e32 v127, 0xbfb8aa3b, v125
	v_mul_f32_e32 v122, 0xbfb8aa3b, v120
	v_mul_f32_e32 v123, 0xbfb8aa3b, v121
	v_exp_f32_e32 v126, v126
	v_exp_f32_e32 v127, v127
	v_exp_f32_e32 v122, v122
	v_exp_f32_e32 v123, v123
	v_add_f32_e32 v126, 1.0, v126
	v_add_f32_e32 v127, 1.0, v127
	v_add_f32_e32 v122, 1.0, v122
	v_add_f32_e32 v123, 1.0, v123
	v_rcp_f32_e32 v126, v126
	v_rcp_f32_e32 v127, v127
	v_rcp_f32_e32 v122, v122
	v_rcp_f32_e32 v123, v123
	v_pk_mul_f32 v[124:125], v[124:125], v[126:127]
	s_nop 0
	v_pk_mul_f32 v[116:117], v[116:117], v[124:125]
	v_pk_mul_f32 v[120:121], v[120:121], v[122:123]
	v_cvt_pk_bf16_f32 v116, v116, v117
	v_pk_mul_f32 v[118:119], v[118:119], v[120:121]
	s_nop 0
	v_cvt_pk_bf16_f32 v117, v118, v119
	v_mov_b64_e32 v[118:119], s[24:25]
	v_mad_i64_i32 v[118:119], s[66:67], v149, s0, v[118:119]
	v_lshl_add_u64 v[118:119], v[172:173], 1, v[118:119]
.LBB0_679:
	s_or_b64 exec, exec, s[54:55]
	v_mov_b32_e32 v244, v116
	v_mov_b32_e32 v245, v117
	s_nop 1
	v_permlane16_swap_b32_e32 v242, v244
	v_permlane16_swap_b32_e32 v243, v245
	s_and_b32 s98, s98, 0xffff
	s_and_b32 s99, s99, 0xffff
	s_and_b32 s100, s100, 0xffff0000
	s_and_b32 s101, s101, 0xffff0000
	s_or_b64 s[98:99], s[98:99], s[100:101]
	s_mov_b64 s[100:101], exec
	s_mov_b64 exec, s[98:99]
	global_store_dwordx4 v[246:247], v[242:245], off
	s_mov_b64 exec, s[100:101]
	s_add_i32 s76, s56, 0x7c
	s_cmpk_gt_u32 s76, 0x3fc0
	s_mov_b64 s[54:55], -1
	s_cselect_b64 s[66:67], -1, 0
	s_cmpk_lt_u32 s76, 0x3fc1
	v_add_u32_e32 v150, s76, v194
	s_cbranch_scc1 .LBB0_681
	v_add_u32_e32 v151, s76, v194
	v_cmp_gt_u32_e32 vcc, s5, v151
	v_add_u32_e32 v116, 16, v151
	s_mov_b64 s[54:55], 0
	v_cndmask_b32_e32 v146, 0, v112, vcc
	v_cndmask_b32_e32 v147, 0, v113, vcc
	v_cndmask_b32_e32 v144, 0, v114, vcc
	v_cndmask_b32_e32 v145, 0, v115, vcc
	v_cmp_gt_u32_e32 vcc, s5, v116
	v_add_u32_e32 v116, 32, v151
	s_nop 0
	v_cndmask_b32_e32 v126, 0, v108, vcc
	v_cndmask_b32_e32 v127, 0, v109, vcc
	v_cndmask_b32_e32 v124, 0, v110, vcc
	v_cndmask_b32_e32 v125, 0, v111, vcc
	v_cmp_gt_u32_e32 vcc, s5, v116
	v_add_u32_e32 v116, 48, v151
	s_nop 0
	v_cndmask_b32_e32 v122, 0, v104, vcc
	v_cndmask_b32_e32 v123, 0, v105, vcc
	v_cndmask_b32_e32 v120, 0, v106, vcc
	v_cndmask_b32_e32 v121, 0, v107, vcc
	v_cmp_gt_u32_e32 vcc, s5, v116
	s_nop 1
	v_cndmask_b32_e32 v118, 0, v100, vcc
	v_cndmask_b32_e32 v119, 0, v101, vcc
	v_cndmask_b32_e32 v116, 0, v102, vcc
	v_cndmask_b32_e32 v117, 0, v103, vcc

; DI unsigned pack2(float a, float b) { f2_t v = {a, b}; return __builtin_bit_cast(unsigned, __builtin_convertvector(v, bf2_t)); }
; DI float exp2_hw(float x) { return __builtin_amdgcn_exp2f(x); }
; DI float dpp_ror1(float v)  { return __builtin_bit_cast(float, __builtin_amdgcn_update_dpp(0, __builtin_bit_cast(int, v), 0x121, 0xf, 0xf, false)); }
; DI float dpp_ror15(float v) { return __builtin_bit_cast(float, __builtin_amdgcn_update_dpp(0, __builtin_bit_cast(int, v), 0x12F, 0xf, 0xf, false)); }
;   DI void operator()(const f32x4 (&acc)[2][2][4][2], const pg8::Unit& u, int wr, int wc, int fr, int fq) const {
;     ...
; #pragma unroll
;         for (int m = 0; m < 4; ++m) {
;           const int q = 16 * m + fr, tok = tokb + q;
;           f32x4 r;
; #pragma unroll
;           for (int e = 0; e < 4; ++e) {
;             const float srcm = (fr == 15 && m > 0) ? g[m > 0 ? m - 1 : 0][e] : g[m][e];
;             const float srcp = (fr == 0 && m < 3) ? g[m < 3 ? m + 1 : 3][e] : g[m][e];
;             const float gm = dpp_ror1(srcm), gp = dpp_ror15(srcp);
;             const float cv = bb[e] + w0[e] * gm + w1[e] * g[m][e] + w2[e] * gp;
;             r[e] = cv * __builtin_amdgcn_rcpf(1.f + exp2_hw(-LOG2E * cv)) * acc[ai][1][m][n][e];
;           }
;           if (q >= 1 && q <= 62 && tok < S)
;             *(uint2*)(act + (size_t)(b * S + tok) * DFF + col) = make_uint2(pack2(r[0], r[1]), pack2(r[2], r[3]));
.LBB0_683:
	v_cndmask_b32_e64 v100, v146, v126, s[42:43]
	v_mov_b32_e32 v106, v1
	v_mov_b32_e32 v107, v1
	v_cndmask_b32_e64 v101, v144, v124, s[42:43]
	v_mov_b32_dpp v106, v100 row_ror:15 row_mask:0xf bank_mask:0xf
	v_cndmask_b32_e64 v100, v147, v127, s[42:43]
	v_mov_b32_e32 v102, v1
	v_mov_b32_e32 v104, v1
	v_mov_b32_e32 v105, v1
	v_mov_b32_dpp v107, v100 row_ror:15 row_mask:0xf bank_mask:0xf
	v_mov_b32_e32 v100, v1
	v_mov_b32_dpp v102, v101 row_ror:15 row_mask:0xf bank_mask:0xf
	v_cndmask_b32_e64 v108, v145, v125, s[42:43]
	v_mov_b32_e32 v101, v1
	v_mov_b32_e32 v103, v1
	v_cmp_gt_i32_e32 vcc, s5, v151
	v_mov_b32_dpp v104, v146 row_ror:1 row_mask:0xf bank_mask:0xf
	v_mov_b32_dpp v105, v147 row_ror:1 row_mask:0xf bank_mask:0xf
	v_mov_b32_dpp v100, v144 row_ror:1 row_mask:0xf bank_mask:0xf
	v_mov_b32_dpp v101, v145 row_ror:1 row_mask:0xf bank_mask:0xf
	v_mov_b32_dpp v103, v108 row_ror:15 row_mask:0xf bank_mask:0xf
	s_and_b64 s[68:69], s[44:45], vcc
	v_add_u32_e32 v150, s59, v151
	s_mov_b64 s[98:99], s[68:69]
	s_and_saveexec_b64 s[54:55], s[68:69]
	s_cbranch_execz .LBB0_685
	s_waitcnt vmcnt(0)
	v_pk_fma_f32 v[104:105], v[128:129], v[104:105], v[140:141]
	v_pk_fma_f32 v[100:101], v[130:131], v[100:101], v[142:143]
	v_pk_fma_f32 v[104:105], v[132:133], v[146:147], v[104:105]
	v_pk_fma_f32 v[100:101], v[134:135], v[144:145], v[100:101]
	v_pk_fma_f32 v[104:105], v[136:137], v[106:107], v[104:105]
	v_pk_fma_f32 v[100:101], v[138:139], v[102:103], v[100:101]
	v_mul_f32_e32 v106, 0xbfb8aa3b, v104
	v_mul_f32_e32 v107, 0xbfb8aa3b, v105
	v_mul_f32_e32 v102, 0xbfb8aa3b, v100
	v_mul_f32_e32 v103, 0xbfb8aa3b, v101
	v_exp_f32_e32 v106, v106
	v_exp_f32_e32 v107, v107
	v_exp_f32_e32 v102, v102
	v_exp_f32_e32 v103, v103
	v_add_f32_e32 v106, 1.0, v106
	v_add_f32_e32 v107, 1.0, v107
	v_add_f32_e32 v102, 1.0, v102
	v_add_f32_e32 v103, 1.0, v103
	v_rcp_f32_e32 v106, v106
	v_rcp_f32_e32 v107, v107
	v_rcp_f32_e32 v102, v102
	v_rcp_f32_e32 v103, v103
	v_pk_mul_f32 v[104:105], v[104:105], v[106:107]
	s_nop 0
	v_pk_mul_f32 v[96:97], v[96:97], v[104:105]
	v_pk_mul_f32 v[100:101], v[100:101], v[102:103]
	v_cvt_pk_bf16_f32 v96, v96, v97
	v_pk_mul_f32 v[98:99], v[98:99], v[100:101]
	s_nop 0
	v_cvt_pk_bf16_f32 v97, v98, v99
	v_mov_b64_e32 v[98:99], s[24:25]
	v_mad_i64_i32 v[98:99], s[56:57], v150, s0, v[98:99]
	v_lshl_add_u64 v[98:99], v[172:173], 1, v[98:99]
.LBB0_685:
	s_or_b64 exec, exec, s[54:55]
	v_mov_b64_e32 v[246:247], s[24:25]
	v_mad_i64_i32 v[246:247], s[100:101], v150, s0, v[246:247]
	v_lshl_add_u64 v[246:247], v[172:173], 1, v[246:247]
	v_bfe_u32 v244, v227, 4, 1
	v_mul_u32_u24_e32 v244, 0x15ff8, v244
	v_mov_b32_e32 v245, 0
	v_lshl_add_u64 v[246:247], v[246:247], 0, v[244:245]
	v_mov_b32_e32 v242, v96
	v_mov_b32_e32 v243, v97
	v_cndmask_b32_e64 v96, v126, v146, s[40:41]
	v_cndmask_b32_e64 v97, v126, v122, s[42:43]
	v_mov_b32_e32 v100, v1
	v_mov_b32_e32 v102, v1
	v_mov_b32_e32 v101, v1
	v_mov_b32_dpp v100, v96 row_ror:1 row_mask:0xf bank_mask:0xf
	v_mov_b32_dpp v102, v97 row_ror:15 row_mask:0xf bank_mask:0xf
	v_cndmask_b32_e64 v96, v127, v147, s[40:41]
	v_cndmask_b32_e64 v97, v127, v123, s[42:43]
	v_mov_b32_e32 v103, v1
	v_mov_b32_dpp v101, v96 row_ror:1 row_mask:0xf bank_mask:0xf
	v_cndmask_b32_e64 v99, v124, v120, s[42:43]
	v_mov_b32_dpp v103, v97 row_ror:15 row_mask:0xf bank_mask:0xf
	v_cndmask_b32_e64 v97, v124, v144, s[40:41]
	v_mov_b32_e32 v96, v1
	v_mov_b32_e32 v98, v1
	v_cndmask_b32_e64 v104, v125, v121, s[42:43]
	v_mov_b32_dpp v96, v97 row_ror:1 row_mask:0xf bank_mask:0xf
	v_mov_b32_dpp v98, v99 row_ror:15 row_mask:0xf bank_mask:0xf
	v_cndmask_b32_e64 v99, v125, v145, s[40:41]
	v_mov_b32_e32 v97, v1
	s_nop 1
	v_mov_b32_dpp v97, v99 row_ror:1 row_mask:0xf bank_mask:0xf
	v_mov_b32_e32 v99, v1
	s_nop 1
	v_mov_b32_dpp v99, v104 row_ror:15 row_mask:0xf bank_mask:0xf
	v_add_u32_e32 v104, s76, v196
	v_cmp_gt_i32_e64 s[54:55], s5, v104
	v_add_u32_e32 v144, s59, v104
	s_mov_b64 s[100:101], s[54:55]
	s_and_saveexec_b64 s[56:57], s[54:55]
	s_cbranch_execz .LBB0_687
	s_waitcnt vmcnt(0)
	v_pk_fma_f32 v[100:101], v[128:129], v[100:101], v[140:141]
	v_pk_fma_f32 v[96:97], v[130:131], v[96:97], v[142:143]
	v_pk_fma_f32 v[100:101], v[132:133], v[126:127], v[100:101]
	v_pk_fma_f32 v[96:97], v[134:135], v[124:125], v[96:97]
	v_pk_fma_f32 v[100:101], v[136:137], v[102:103], v[100:101]
	v_pk_fma_f32 v[96:97], v[138:139], v[98:99], v[96:97]
	v_mul_f32_e32 v102, 0xbfb8aa3b, v100
	v_mul_f32_e32 v103, 0xbfb8aa3b, v101
	v_mul_f32_e32 v98, 0xbfb8aa3b, v96
	v_mul_f32_e32 v99, 0xbfb8aa3b, v97
	v_exp_f32_e32 v102, v102
	v_exp_f32_e32 v103, v103
	v_exp_f32_e32 v98, v98
	v_exp_f32_e32 v99, v99
	v_add_f32_e32 v102, 1.0, v102
	v_add_f32_e32 v103, 1.0, v103
	v_add_f32_e32 v98, 1.0, v98
	v_add_f32_e32 v99, 1.0, v99
	v_rcp_f32_e32 v102, v102
	v_rcp_f32_e32 v103, v103
	v_rcp_f32_e32 v98, v98
	v_rcp_f32_e32 v99, v99
	v_pk_mul_f32 v[100:101], v[100:101], v[102:103]
	s_nop 0
	v_pk_mul_f32 v[92:93], v[92:93], v[100:101]
	v_pk_mul_f32 v[96:97], v[96:97], v[98:99]
	v_cvt_pk_bf16_f32 v92, v92, v93
	v_pk_mul_f32 v[94:95], v[94:95], v[96:97]
	s_nop 0
	v_cvt_pk_bf16_f32 v93, v94, v95
	v_mov_b64_e32 v[94:95], s[24:25]
	v_mad_i64_i32 v[94:95], s[72:73], v144, s0, v[94:95]
	v_lshl_add_u64 v[94:95], v[172:173], 1, v[94:95]
; DI unsigned pack2(float a, float b) { f2_t v = {a, b}; return __builtin_bit_cast(unsigned, __builtin_convertvector(v, bf2_t)); }
; DI float exp2_hw(float x) { return __builtin_amdgcn_exp2f(x); }
; DI float dpp_ror1(float v)  { return __builtin_bit_cast(float, __builtin_amdgcn_update_dpp(0, __builtin_bit_cast(int, v), 0x121, 0xf, 0xf, false)); }
; DI float dpp_ror15(float v) { return __builtin_bit_cast(float, __builtin_amdgcn_update_dpp(0, __builtin_bit_cast(int, v), 0x12F, 0xf, 0xf, false)); }
;   DI void operator()(const f32x4 (&acc)[2][2][4][2], const pg8::Unit& u, int wr, int wc, int fr, int fq) const {
;     ...
; #pragma unroll
;         for (int m = 0; m < 4; ++m) {
;           const int q = 16 * m + fr, tok = tokb + q;
;           f32x4 r;
; #pragma unroll
;           for (int e = 0; e < 4; ++e) {
;             const float srcm = (fr == 15 && m > 0) ? g[m > 0 ? m - 1 : 0][e] : g[m][e];
;             const float srcp = (fr == 0 && m < 3) ? g[m < 3 ? m + 1 : 3][e] : g[m][e];
;             const float gm = dpp_ror1(srcm), gp = dpp_ror15(srcp);
;             const float cv = bb[e] + w0[e] * gm + w1[e] * g[m][e] + w2[e] * gp;
;             r[e] = cv * __builtin_amdgcn_rcpf(1.f + exp2_hw(-LOG2E * cv)) * acc[ai][1][m][n][e];
;           }
;           if (q >= 1 && q <= 62 && tok < S)
;             *(uint2*)(act + (size_t)(b * S + tok) * DFF + col) = make_uint2(pack2(r[0], r[1]), pack2(r[2], r[3]));
.LBB0_687:
	s_or_b64 exec, exec, s[56:57]
	v_mov_b32_e32 v244, v92
	v_mov_b32_e32 v245, v93
	s_nop 1
	v_permlane16_swap_b32_e32 v242, v244
	v_permlane16_swap_b32_e32 v243, v245
	s_and_b32 s98, s98, 0xffff
	s_and_b32 s99, s99, 0xffff
	s_and_b32 s100, s100, 0xffff0000
	s_and_b32 s101, s101, 0xffff0000
	s_or_b64 s[98:99], s[98:99], s[100:101]
	s_mov_b64 s[100:101], exec
	s_mov_b64 exec, s[98:99]
	global_store_dwordx4 v[246:247], v[242:245], off
	s_mov_b64 exec, s[100:101]
	v_cndmask_b32_e64 v92, v122, v126, s[40:41]
	v_cndmask_b32_e64 v93, v122, v118, s[42:43]
	v_mov_b32_e32 v96, v1
	v_mov_b32_e32 v98, v1
	v_mov_b32_e32 v97, v1
	v_mov_b32_dpp v96, v92 row_ror:1 row_mask:0xf bank_mask:0xf
	v_mov_b32_dpp v98, v93 row_ror:15 row_mask:0xf bank_mask:0xf
	v_cndmask_b32_e64 v92, v123, v127, s[40:41]
	v_cndmask_b32_e64 v93, v123, v119, s[42:43]
	v_mov_b32_e32 v99, v1
	v_mov_b32_dpp v97, v92 row_ror:1 row_mask:0xf bank_mask:0xf
	v_cndmask_b32_e64 v95, v120, v116, s[42:43]
	v_mov_b32_dpp v99, v93 row_ror:15 row_mask:0xf bank_mask:0xf
	v_cndmask_b32_e64 v93, v120, v124, s[40:41]
	v_mov_b32_e32 v92, v1
	v_mov_b32_e32 v94, v1
	v_cndmask_b32_e64 v100, v121, v117, s[42:43]
	v_mov_b32_dpp v92, v93 row_ror:1 row_mask:0xf bank_mask:0xf
	v_mov_b32_dpp v94, v95 row_ror:15 row_mask:0xf bank_mask:0xf
	v_cndmask_b32_e64 v95, v121, v125, s[40:41]
	v_mov_b32_e32 v93, v1
	s_nop 1
	v_mov_b32_dpp v93, v95 row_ror:1 row_mask:0xf bank_mask:0xf
	v_mov_b32_e32 v95, v1
	s_nop 1
	v_mov_b32_dpp v95, v100 row_ror:15 row_mask:0xf bank_mask:0xf
	v_add_u32_e32 v100, s76, v197
	v_cmp_gt_i32_e64 s[56:57], s5, v100
	v_add_u32_e32 v124, s59, v100
	s_mov_b64 s[98:99], s[56:57]
	s_and_saveexec_b64 s[72:73], s[56:57]
	s_cbranch_execz .LBB0_689
	s_waitcnt vmcnt(0)
	v_pk_fma_f32 v[96:97], v[128:129], v[96:97], v[140:141]
	v_pk_fma_f32 v[92:93], v[130:131], v[92:93], v[142:143]
	v_pk_fma_f32 v[96:97], v[132:133], v[122:123], v[96:97]
	v_pk_fma_f32 v[92:93], v[134:135], v[120:121], v[92:93]
	v_pk_fma_f32 v[96:97], v[136:137], v[98:99], v[96:97]
	v_pk_fma_f32 v[92:93], v[138:139], v[94:95], v[92:93]
	v_mul_f32_e32 v98, 0xbfb8aa3b, v96
	v_mul_f32_e32 v99, 0xbfb8aa3b, v97
	v_mul_f32_e32 v94, 0xbfb8aa3b, v92
	v_mul_f32_e32 v95, 0xbfb8aa3b, v93
	v_exp_f32_e32 v98, v98
	v_exp_f32_e32 v99, v99
	v_exp_f32_e32 v94, v94
	v_exp_f32_e32 v95, v95
	v_add_f32_e32 v98, 1.0, v98
	v_add_f32_e32 v99, 1.0, v99
	v_add_f32_e32 v94, 1.0, v94
	v_add_f32_e32 v95, 1.0, v95
	v_rcp_f32_e32 v98, v98
	v_rcp_f32_e32 v99, v99
	v_rcp_f32_e32 v94, v94
	v_rcp_f32_e32 v95, v95
	v_pk_mul_f32 v[96:97], v[96:97], v[98:99]
	s_nop 0
	v_pk_mul_f32 v[88:89], v[88:89], v[96:97]
	v_pk_mul_f32 v[92:93], v[92:93], v[94:95]
	v_cvt_pk_bf16_f32 v88, v88, v89
	v_pk_mul_f32 v[90:91], v[90:91], v[92:93]
	s_nop 0
	v_cvt_pk_bf16_f32 v89, v90, v91
	v_mov_b64_e32 v[90:91], s[24:25]
	v_mad_i64_i32 v[90:91], vcc, v124, s0, v[90:91]
	v_lshl_add_u64 v[90:91], v[172:173], 1, v[90:91]
; DI unsigned pack2(float a, float b) { f2_t v = {a, b}; return __builtin_bit_cast(unsigned, __builtin_convertvector(v, bf2_t)); }
; DI float exp2_hw(float x) { return __builtin_amdgcn_exp2f(x); }
; DI float dpp_ror1(float v)  { return __builtin_bit_cast(float, __builtin_amdgcn_update_dpp(0, __builtin_bit_cast(int, v), 0x121, 0xf, 0xf, false)); }
; DI float dpp_ror15(float v) { return __builtin_bit_cast(float, __builtin_amdgcn_update_dpp(0, __builtin_bit_cast(int, v), 0x12F, 0xf, 0xf, false)); }
;   DI void operator()(const f32x4 (&acc)[2][2][4][2], const pg8::Unit& u, int wr, int wc, int fr, int fq) const {
;     ...
;     for (int n = 0; n < 2; ++n) {
;       const int col = u.pn * 128 + wc * 32 + n * 16 + 4 * fq;
;       const f32x4 w0 = *(const f32x4*)(cw + col), w1 = *(const f32x4*)(cw + DFF + col), w2 = *(const f32x4*)(cw + 2 * DFF + col), bb = *(const f32x4*)(cb + col);
; #pragma unroll
;       for (int ai = 0; ai < 2; ++ai) {
;         const int tokb = 248 * ti - 1 + 62 * (2 * ai + wr);
;         f32x4 g[4];
;         if (tokb >= 0 && tokb + 63 < S) {
; #pragma unroll
;           for (int m = 0; m < 4; ++m) g[m] = acc[ai][0][m][n];
;         } else {
; #pragma unroll
;           for (int m = 0; m < 4; ++m) {
;             const int tok = tokb + 16 * m + fr;
;             const bool ok = (tok >= 0) && (tok < S);
; #pragma unroll
;             for (int e = 0; e < 4; ++e) g[m][e] = ok ? acc[ai][0][m][n][e] : 0.f;
;           }
;         }
; #pragma unroll
;         for (int m = 0; m < 4; ++m) {
;           const int q = 16 * m + fr, tok = tokb + q;
;           f32x4 r;
; #pragma unroll
;           for (int e = 0; e < 4; ++e) {
;             const float srcm = (fr == 15 && m > 0) ? g[m > 0 ? m - 1 : 0][e] : g[m][e];
;             const float srcp = (fr == 0 && m < 3) ? g[m < 3 ? m + 1 : 3][e] : g[m][e];
;             const float gm = dpp_ror1(srcm), gp = dpp_ror15(srcp);
;             const float cv = bb[e] + w0[e] * gm + w1[e] * g[m][e] + w2[e] * gp;
;             r[e] = cv * __builtin_amdgcn_rcpf(1.f + exp2_hw(-LOG2E * cv)) * acc[ai][1][m][n][e];
;           }
;           if (q >= 1 && q <= 62 && tok < S)
;             *(uint2*)(act + (size_t)(b * S + tok) * DFF + col) = make_uint2(pack2(r[0], r[1]), pack2(r[2], r[3]));
.LBB0_689:
	s_or_b64 exec, exec, s[72:73]
	v_mov_b64_e32 v[246:247], s[24:25]
	v_mad_i64_i32 v[246:247], s[100:101], v124, s0, v[246:247]
	v_lshl_add_u64 v[246:247], v[172:173], 1, v[246:247]
	v_bfe_u32 v244, v227, 4, 1
	v_mul_u32_u24_e32 v244, 0x15ff8, v244
	v_mov_b32_e32 v245, 0
	v_lshl_add_u64 v[246:247], v[246:247], 0, v[244:245]
	v_mov_b32_e32 v242, v88
	v_mov_b32_e32 v243, v89
	v_cndmask_b32_e64 v88, v118, v122, s[40:41]
	v_mov_b32_e32 v92, v1
	v_mov_b32_e32 v93, v1
	v_cndmask_b32_e64 v89, v116, v120, s[40:41]
	v_mov_b32_dpp v92, v88 row_ror:1 row_mask:0xf bank_mask:0xf
	v_cndmask_b32_e64 v88, v119, v123, s[40:41]
	v_cndmask_b32_e64 v91, v117, v121, s[40:41]
	v_add_u32_e32 v96, s76, v198
	v_mov_b32_dpp v93, v88 row_ror:1 row_mask:0xf bank_mask:0xf
	v_mov_b32_e32 v88, v1
	v_mov_b32_e32 v94, v1
	v_mov_b32_e32 v95, v1
	v_mov_b32_dpp v88, v89 row_ror:1 row_mask:0xf bank_mask:0xf
	v_mov_b32_e32 v89, v1
	v_mov_b32_e32 v90, v1
	v_cmp_gt_i32_e32 vcc, s5, v96
	v_mov_b32_dpp v89, v91 row_ror:1 row_mask:0xf bank_mask:0xf
	v_mov_b32_e32 v91, v1
	v_mov_b32_dpp v94, v118 row_ror:15 row_mask:0xf bank_mask:0xf
	v_mov_b32_dpp v95, v119 row_ror:15 row_mask:0xf bank_mask:0xf
	v_mov_b32_dpp v90, v116 row_ror:15 row_mask:0xf bank_mask:0xf
	v_mov_b32_dpp v91, v117 row_ror:15 row_mask:0xf bank_mask:0xf
	s_and_b64 s[72:73], s[46:47], vcc
	v_add_u32_e32 v120, s59, v96
	s_mov_b64 s[100:101], s[72:73]
	s_and_saveexec_b64 s[76:77], s[72:73]
	s_cbranch_execz .LBB0_691
	s_waitcnt vmcnt(0)
	v_pk_fma_f32 v[92:93], v[128:129], v[92:93], v[140:141]
	v_pk_fma_f32 v[88:89], v[130:131], v[88:89], v[142:143]
	v_pk_fma_f32 v[92:93], v[132:133], v[118:119], v[92:93]
	v_pk_fma_f32 v[88:89], v[134:135], v[116:117], v[88:89]
	v_pk_fma_f32 v[92:93], v[136:137], v[94:95], v[92:93]
	v_pk_fma_f32 v[88:89], v[138:139], v[90:91], v[88:89]
	v_mul_f32_e32 v94, 0xbfb8aa3b, v92
	v_mul_f32_e32 v95, 0xbfb8aa3b, v93
	v_mul_f32_e32 v90, 0xbfb8aa3b, v88
	v_mul_f32_e32 v91, 0xbfb8aa3b, v89
	v_exp_f32_e32 v94, v94
	v_exp_f32_e32 v95, v95
	v_exp_f32_e32 v90, v90
	v_exp_f32_e32 v91, v91
	v_add_f32_e32 v94, 1.0, v94
	v_add_f32_e32 v95, 1.0, v95
	v_add_f32_e32 v90, 1.0, v90
	v_add_f32_e32 v91, 1.0, v91
	v_rcp_f32_e32 v94, v94
	v_rcp_f32_e32 v95, v95
	v_rcp_f32_e32 v90, v90
	v_rcp_f32_e32 v91, v91
	v_pk_mul_f32 v[92:93], v[92:93], v[94:95]
	s_nop 0
	v_pk_mul_f32 v[84:85], v[84:85], v[92:93]
	v_pk_mul_f32 v[88:89], v[88:89], v[90:91]
	v_cvt_pk_bf16_f32 v84, v84, v85
	v_pk_mul_f32 v[86:87], v[86:87], v[88:89]
	s_nop 0
	v_cvt_pk_bf16_f32 v85, v86, v87
	v_mov_b64_e32 v[86:87], s[24:25]
	v_mad_i64_i32 v[86:87], vcc, v120, s0, v[86:87]
	v_lshl_add_u64 v[86:87], v[172:173], 1, v[86:87]
.LBB0_691:
	s_or_b64 exec, exec, s[76:77]
	v_mov_b32_e32 v244, v84
	v_mov_b32_e32 v245, v85
	s_nop 1
	v_permlane16_swap_b32_e32 v242, v244
	v_permlane16_swap_b32_e32 v243, v245
	s_and_b32 s98, s98, 0xffff
	s_and_b32 s99, s99, 0xffff
	s_and_b32 s100, s100, 0xffff0000
	s_and_b32 s101, s101, 0xffff0000
	s_or_b64 s[98:99], s[98:99], s[100:101]
	s_mov_b64 s[100:101], exec
	s_mov_b64 exec, s[98:99]
	global_store_dwordx4 v[246:247], v[242:245], off
	s_mov_b64 exec, s[100:101]
	v_or_b32_e32 v88, 16, v172
	v_ashrrev_i32_e32 v89, 31, v88
	v_lshlrev_b64 v[88:89], 2, v[88:89]
	v_lshl_add_u64 v[90:91], s[30:31], 0, v[88:89]
	v_lshl_add_u64 v[92:93], s[34:35], 0, v[88:89]
	global_load_dwordx4 v[84:87], v[174:175], off offset:64
	s_nop 0
	global_load_dwordx4 v[88:91], v[90:91], off
	s_nop 0
	global_load_dwordx4 v[92:95], v[92:93], off
	s_nop 0
	global_load_dwordx4 v[96:99], v[176:177], off offset:64
	s_andn2_b64 vcc, exec, s[16:17]
	s_mov_b64 s[16:17], -1
	s_cbranch_vccnz .LBB0_693
	v_cmp_gt_u32_e32 vcc, s5, v201
	v_add_u32_e32 v100, 16, v201
	s_mov_b64 s[16:17], 0
	v_cndmask_b32_e32 v114, 0, v80, vcc
	v_cndmask_b32_e32 v115, 0, v81, vcc
	v_cndmask_b32_e32 v112, 0, v82, vcc
	v_cndmask_b32_e32 v113, 0, v83, vcc
	v_cmp_gt_u32_e32 vcc, s5, v100
	v_add_u32_e32 v100, 32, v201
	s_nop 0
	v_cndmask_b32_e32 v110, 0, v76, vcc
	v_cndmask_b32_e32 v111, 0, v77, vcc
	v_cndmask_b32_e32 v108, 0, v78, vcc
	v_cndmask_b32_e32 v109, 0, v79, vcc
	v_cmp_gt_u32_e32 vcc, s5, v100
	v_add_u32_e32 v100, 48, v201
	s_nop 0
	v_cndmask_b32_e32 v106, 0, v72, vcc
	v_cndmask_b32_e32 v107, 0, v73, vcc
	v_cndmask_b32_e32 v104, 0, v74, vcc
	v_cndmask_b32_e32 v105, 0, v75, vcc
	v_cmp_gt_u32_e32 vcc, s5, v100
	s_nop 1
	v_cndmask_b32_e32 v102, 0, v68, vcc
	v_cndmask_b32_e32 v103, 0, v69, vcc
	v_cndmask_b32_e32 v100, 0, v70, vcc
	v_cndmask_b32_e32 v101, 0, v71, vcc

; DI unsigned pack2(float a, float b) { f2_t v = {a, b}; return __builtin_bit_cast(unsigned, __builtin_convertvector(v, bf2_t)); }
; DI float exp2_hw(float x) { return __builtin_amdgcn_exp2f(x); }
; DI float dpp_ror1(float v)  { return __builtin_bit_cast(float, __builtin_amdgcn_update_dpp(0, __builtin_bit_cast(int, v), 0x121, 0xf, 0xf, false)); }
; DI float dpp_ror15(float v) { return __builtin_bit_cast(float, __builtin_amdgcn_update_dpp(0, __builtin_bit_cast(int, v), 0x12F, 0xf, 0xf, false)); }
;   DI void operator()(const f32x4 (&acc)[2][2][4][2], const pg8::Unit& u, int wr, int wc, int fr, int fq) const {
;     ...
; #pragma unroll
;         for (int m = 0; m < 4; ++m) {
;           const int q = 16 * m + fr, tok = tokb + q;
;           f32x4 r;
; #pragma unroll
;           for (int e = 0; e < 4; ++e) {
;             const float srcm = (fr == 15 && m > 0) ? g[m > 0 ? m - 1 : 0][e] : g[m][e];
;             const float srcp = (fr == 0 && m < 3) ? g[m < 3 ? m + 1 : 3][e] : g[m][e];
;             const float gm = dpp_ror1(srcm), gp = dpp_ror15(srcp);
;             const float cv = bb[e] + w0[e] * gm + w1[e] * g[m][e] + w2[e] * gp;
;             r[e] = cv * __builtin_amdgcn_rcpf(1.f + exp2_hw(-LOG2E * cv)) * acc[ai][1][m][n][e];
;           }
;           if (q >= 1 && q <= 62 && tok < S)
;             *(uint2*)(act + (size_t)(b * S + tok) * DFF + col) = make_uint2(pack2(r[0], r[1]), pack2(r[2], r[3]));
.LBB0_695:
	v_cndmask_b32_e64 v68, v114, v110, s[42:43]
	v_mov_b32_e32 v74, v1
	v_mov_b32_e32 v75, v1
	v_cndmask_b32_e64 v69, v112, v108, s[42:43]
	v_mov_b32_dpp v74, v68 row_ror:15 row_mask:0xf bank_mask:0xf
	v_cndmask_b32_e64 v68, v115, v111, s[42:43]
	v_mov_b32_e32 v70, v1
	v_mov_b32_e32 v72, v1
	v_mov_b32_e32 v73, v1
	v_mov_b32_dpp v75, v68 row_ror:15 row_mask:0xf bank_mask:0xf
	v_mov_b32_e32 v68, v1
	v_mov_b32_dpp v70, v69 row_ror:15 row_mask:0xf bank_mask:0xf
	v_cndmask_b32_e64 v76, v113, v109, s[42:43]
	v_mov_b32_e32 v69, v1
	v_mov_b32_e32 v71, v1
	v_mov_b32_dpp v72, v114 row_ror:1 row_mask:0xf bank_mask:0xf
	v_mov_b32_dpp v73, v115 row_ror:1 row_mask:0xf bank_mask:0xf
	v_mov_b32_dpp v68, v112 row_ror:1 row_mask:0xf bank_mask:0xf
	v_mov_b32_dpp v69, v113 row_ror:1 row_mask:0xf bank_mask:0xf
	v_mov_b32_dpp v71, v76 row_ror:15 row_mask:0xf bank_mask:0xf
	s_mov_b64 s[98:99], s[36:37]
	s_and_saveexec_b64 s[16:17], s[36:37]
	s_cbranch_execz .LBB0_697
	s_waitcnt vmcnt(0)
	v_pk_fma_f32 v[72:73], v[84:85], v[72:73], v[96:97]
	v_pk_fma_f32 v[68:69], v[86:87], v[68:69], v[98:99]
	v_pk_fma_f32 v[72:73], v[88:89], v[114:115], v[72:73]
	v_pk_fma_f32 v[68:69], v[90:91], v[112:113], v[68:69]
	v_pk_fma_f32 v[72:73], v[92:93], v[74:75], v[72:73]
	v_pk_fma_f32 v[68:69], v[94:95], v[70:71], v[68:69]
	v_mul_f32_e32 v74, 0xbfb8aa3b, v72
	v_mul_f32_e32 v75, 0xbfb8aa3b, v73
	v_mul_f32_e32 v70, 0xbfb8aa3b, v68
	v_mul_f32_e32 v71, 0xbfb8aa3b, v69
	v_exp_f32_e32 v74, v74
	v_exp_f32_e32 v75, v75
	v_exp_f32_e32 v70, v70
	v_exp_f32_e32 v71, v71
	v_add_f32_e32 v74, 1.0, v74
	v_add_f32_e32 v75, 1.0, v75
	v_add_f32_e32 v70, 1.0, v70
	v_add_f32_e32 v71, 1.0, v71
	v_rcp_f32_e32 v74, v74
	v_rcp_f32_e32 v75, v75
	v_rcp_f32_e32 v70, v70
	v_rcp_f32_e32 v71, v71
	v_pk_mul_f32 v[72:73], v[72:73], v[74:75]
	s_nop 0
	v_pk_mul_f32 v[64:65], v[64:65], v[72:73]
	v_pk_mul_f32 v[68:69], v[68:69], v[70:71]
	v_cvt_pk_bf16_f32 v64, v64, v65
	v_pk_mul_f32 v[66:67], v[66:67], v[68:69]
	s_nop 0
	v_cvt_pk_bf16_f32 v65, v66, v67
	v_mov_b64_e32 v[66:67], s[24:25]
	v_mad_i64_i32 v[66:67], s[36:37], v156, s0, v[66:67]
	v_lshl_add_u64 v[66:67], v[172:173], 1, v[66:67]
.LBB0_697:
	s_or_b64 exec, exec, s[16:17]
	v_mov_b64_e32 v[246:247], s[24:25]
	v_mad_i64_i32 v[246:247], s[100:101], v156, s0, v[246:247]
	v_lshl_add_u64 v[246:247], v[172:173], 1, v[246:247]
	v_bfe_u32 v244, v227, 4, 1
	v_mul_u32_u24_e32 v244, 0x15ff8, v244
	v_mov_b32_e32 v245, 0
	v_lshl_add_u64 v[246:247], v[246:247], 0, v[244:245]
	v_mov_b32_e32 v242, v64
	v_mov_b32_e32 v243, v65
	v_cndmask_b32_e64 v64, v110, v114, s[40:41]
	v_cndmask_b32_e64 v65, v110, v106, s[42:43]
	v_mov_b32_e32 v68, v1
	v_mov_b32_e32 v70, v1
	v_mov_b32_e32 v69, v1
	v_mov_b32_dpp v68, v64 row_ror:1 row_mask:0xf bank_mask:0xf
	v_mov_b32_dpp v70, v65 row_ror:15 row_mask:0xf bank_mask:0xf
	v_cndmask_b32_e64 v64, v111, v115, s[40:41]
	v_cndmask_b32_e64 v65, v111, v107, s[42:43]
	v_mov_b32_e32 v71, v1
	v_mov_b32_dpp v69, v64 row_ror:1 row_mask:0xf bank_mask:0xf
	v_cndmask_b32_e64 v67, v108, v104, s[42:43]
	v_mov_b32_dpp v71, v65 row_ror:15 row_mask:0xf bank_mask:0xf
	v_cndmask_b32_e64 v65, v108, v112, s[40:41]
	v_mov_b32_e32 v64, v1
	v_mov_b32_e32 v66, v1
	v_cndmask_b32_e64 v72, v109, v105, s[42:43]
	v_mov_b32_dpp v64, v65 row_ror:1 row_mask:0xf bank_mask:0xf
	v_mov_b32_dpp v66, v67 row_ror:15 row_mask:0xf bank_mask:0xf
	v_cndmask_b32_e64 v67, v109, v113, s[40:41]
	v_mov_b32_e32 v65, v1
	s_nop 1
	v_mov_b32_dpp v65, v67 row_ror:1 row_mask:0xf bank_mask:0xf
	v_mov_b32_e32 v67, v1
	s_nop 1
	v_mov_b32_dpp v67, v72 row_ror:15 row_mask:0xf bank_mask:0xf
	s_mov_b64 s[100:101], s[50:51]
	s_and_saveexec_b64 s[16:17], s[50:51]
	s_cbranch_execz .LBB0_699
	s_waitcnt vmcnt(0)
	v_pk_fma_f32 v[68:69], v[84:85], v[68:69], v[96:97]
	v_pk_fma_f32 v[64:65], v[86:87], v[64:65], v[98:99]
	v_pk_fma_f32 v[68:69], v[88:89], v[110:111], v[68:69]
	v_pk_fma_f32 v[64:65], v[90:91], v[108:109], v[64:65]
	v_pk_fma_f32 v[68:69], v[92:93], v[70:71], v[68:69]
	v_pk_fma_f32 v[64:65], v[94:95], v[66:67], v[64:65]
	v_mul_f32_e32 v70, 0xbfb8aa3b, v68
	v_mul_f32_e32 v71, 0xbfb8aa3b, v69
	v_mul_f32_e32 v66, 0xbfb8aa3b, v64
	v_mul_f32_e32 v67, 0xbfb8aa3b, v65
	v_exp_f32_e32 v70, v70
	v_exp_f32_e32 v71, v71
	v_exp_f32_e32 v66, v66
	v_exp_f32_e32 v67, v67
	v_add_f32_e32 v70, 1.0, v70
	v_add_f32_e32 v71, 1.0, v71
	v_add_f32_e32 v66, 1.0, v66
	v_add_f32_e32 v67, 1.0, v67
	v_rcp_f32_e32 v70, v70
	v_rcp_f32_e32 v71, v71
	v_rcp_f32_e32 v66, v66
	v_rcp_f32_e32 v67, v67
	v_pk_mul_f32 v[68:69], v[68:69], v[70:71]
	s_nop 0
	v_pk_mul_f32 v[60:61], v[60:61], v[68:69]
	v_pk_mul_f32 v[64:65], v[64:65], v[66:67]
	v_cvt_pk_bf16_f32 v60, v60, v61
	v_pk_mul_f32 v[62:63], v[62:63], v[64:65]
	s_nop 0
	v_cvt_pk_bf16_f32 v61, v62, v63
	v_mov_b64_e32 v[62:63], s[24:25]
	v_mad_i64_i32 v[62:63], s[36:37], v152, s0, v[62:63]
	v_lshl_add_u64 v[62:63], v[172:173], 1, v[62:63]
; DI unsigned pack2(float a, float b) { f2_t v = {a, b}; return __builtin_bit_cast(unsigned, __builtin_convertvector(v, bf2_t)); }
; DI float exp2_hw(float x) { return __builtin_amdgcn_exp2f(x); }
; DI float dpp_ror1(float v)  { return __builtin_bit_cast(float, __builtin_amdgcn_update_dpp(0, __builtin_bit_cast(int, v), 0x121, 0xf, 0xf, false)); }
; DI float dpp_ror15(float v) { return __builtin_bit_cast(float, __builtin_amdgcn_update_dpp(0, __builtin_bit_cast(int, v), 0x12F, 0xf, 0xf, false)); }
;   DI void operator()(const f32x4 (&acc)[2][2][4][2], const pg8::Unit& u, int wr, int wc, int fr, int fq) const {
;     ...
;         if (tokb >= 0 && tokb + 63 < S) {
; #pragma unroll
;           for (int m = 0; m < 4; ++m) g[m] = acc[ai][0][m][n];
;         } else {
; #pragma unroll
;           for (int m = 0; m < 4; ++m) {
;             const int tok = tokb + 16 * m + fr;
;             const bool ok = (tok >= 0) && (tok < S);
; #pragma unroll
;             for (int e = 0; e < 4; ++e) g[m][e] = ok ? acc[ai][0][m][n][e] : 0.f;
;           }
;     ...
; #pragma unroll
;         for (int m = 0; m < 4; ++m) {
;           const int q = 16 * m + fr, tok = tokb + q;
;           f32x4 r;
; #pragma unroll
;           for (int e = 0; e < 4; ++e) {
;             const float srcm = (fr == 15 && m > 0) ? g[m > 0 ? m - 1 : 0][e] : g[m][e];
;             const float srcp = (fr == 0 && m < 3) ? g[m < 3 ? m + 1 : 3][e] : g[m][e];
;             const float gm = dpp_ror1(srcm), gp = dpp_ror15(srcp);
;             const float cv = bb[e] + w0[e] * gm + w1[e] * g[m][e] + w2[e] * gp;
;             r[e] = cv * __builtin_amdgcn_rcpf(1.f + exp2_hw(-LOG2E * cv)) * acc[ai][1][m][n][e];
;           }
;           if (q >= 1 && q <= 62 && tok < S)
;             *(uint2*)(act + (size_t)(b * S + tok) * DFF + col) = make_uint2(pack2(r[0], r[1]), pack2(r[2], r[3]));
;         }
.LBB0_699:
	s_or_b64 exec, exec, s[16:17]
	v_mov_b32_e32 v244, v60
	v_mov_b32_e32 v245, v61
	s_nop 1
	v_permlane16_swap_b32_e32 v242, v244
	v_permlane16_swap_b32_e32 v243, v245
	s_and_b32 s98, s98, 0xffff
	s_and_b32 s99, s99, 0xffff
	s_and_b32 s100, s100, 0xffff0000
	s_and_b32 s101, s101, 0xffff0000
	s_or_b64 s[98:99], s[98:99], s[100:101]
	s_mov_b64 s[100:101], exec
	s_mov_b64 exec, s[98:99]
	global_store_dwordx4 v[246:247], v[242:245], off offset:32
	s_mov_b64 exec, s[100:101]
	v_cndmask_b32_e64 v60, v106, v110, s[40:41]
	v_cndmask_b32_e64 v61, v106, v102, s[42:43]
	v_mov_b32_e32 v64, v1
	v_mov_b32_e32 v66, v1
	v_mov_b32_e32 v65, v1
	v_mov_b32_dpp v64, v60 row_ror:1 row_mask:0xf bank_mask:0xf
	v_mov_b32_dpp v66, v61 row_ror:15 row_mask:0xf bank_mask:0xf
	v_cndmask_b32_e64 v60, v107, v111, s[40:41]
	v_cndmask_b32_e64 v61, v107, v103, s[42:43]
	v_mov_b32_e32 v67, v1
	v_mov_b32_dpp v65, v60 row_ror:1 row_mask:0xf bank_mask:0xf
	v_cndmask_b32_e64 v63, v104, v100, s[42:43]
	v_mov_b32_dpp v67, v61 row_ror:15 row_mask:0xf bank_mask:0xf
	v_cndmask_b32_e64 v61, v104, v108, s[40:41]
	v_mov_b32_e32 v60, v1
	v_mov_b32_e32 v62, v1
	v_cndmask_b32_e64 v68, v105, v101, s[42:43]
	v_mov_b32_dpp v60, v61 row_ror:1 row_mask:0xf bank_mask:0xf
	v_mov_b32_dpp v62, v63 row_ror:15 row_mask:0xf bank_mask:0xf
	v_cndmask_b32_e64 v63, v105, v109, s[40:41]
	v_mov_b32_e32 v61, v1
	s_nop 1
	v_mov_b32_dpp v61, v63 row_ror:1 row_mask:0xf bank_mask:0xf
	v_mov_b32_e32 v63, v1
	s_nop 1
	v_mov_b32_dpp v63, v68 row_ror:15 row_mask:0xf bank_mask:0xf
	s_mov_b64 s[98:99], s[52:53]
	s_and_saveexec_b64 s[16:17], s[52:53]
	s_cbranch_execz .LBB0_701
	s_waitcnt vmcnt(0)
	v_pk_fma_f32 v[64:65], v[84:85], v[64:65], v[96:97]
	v_pk_fma_f32 v[60:61], v[86:87], v[60:61], v[98:99]
	v_pk_fma_f32 v[64:65], v[88:89], v[106:107], v[64:65]
	v_pk_fma_f32 v[60:61], v[90:91], v[104:105], v[60:61]
	v_pk_fma_f32 v[64:65], v[92:93], v[66:67], v[64:65]
	v_pk_fma_f32 v[60:61], v[94:95], v[62:63], v[60:61]
	v_mul_f32_e32 v66, 0xbfb8aa3b, v64
	v_mul_f32_e32 v67, 0xbfb8aa3b, v65
	v_mul_f32_e32 v62, 0xbfb8aa3b, v60
	v_mul_f32_e32 v63, 0xbfb8aa3b, v61
	v_exp_f32_e32 v66, v66
	v_exp_f32_e32 v67, v67
	v_exp_f32_e32 v62, v62
	v_exp_f32_e32 v63, v63
	v_add_f32_e32 v66, 1.0, v66
	v_add_f32_e32 v67, 1.0, v67
	v_add_f32_e32 v62, 1.0, v62
	v_add_f32_e32 v63, 1.0, v63
	v_rcp_f32_e32 v66, v66
	v_rcp_f32_e32 v67, v67
	v_rcp_f32_e32 v62, v62
	v_rcp_f32_e32 v63, v63
	v_pk_mul_f32 v[64:65], v[64:65], v[66:67]
	s_nop 0
	v_pk_mul_f32 v[56:57], v[56:57], v[64:65]
	v_pk_mul_f32 v[60:61], v[60:61], v[62:63]
	v_cvt_pk_bf16_f32 v56, v56, v57
	v_pk_mul_f32 v[58:59], v[58:59], v[60:61]
	s_nop 0
	v_cvt_pk_bf16_f32 v57, v58, v59
	v_mov_b64_e32 v[58:59], s[24:25]
	v_mad_i64_i32 v[58:59], s[36:37], v148, s0, v[58:59]
	v_lshl_add_u64 v[58:59], v[172:173], 1, v[58:59]
.LBB0_701:
	s_or_b64 exec, exec, s[16:17]
	v_mov_b64_e32 v[246:247], s[24:25]
	v_mad_i64_i32 v[246:247], s[100:101], v148, s0, v[246:247]
	v_lshl_add_u64 v[246:247], v[172:173], 1, v[246:247]
	v_bfe_u32 v244, v227, 4, 1
	v_mul_u32_u24_e32 v244, 0x15ff8, v244
	v_mov_b32_e32 v245, 0
	v_lshl_add_u64 v[246:247], v[246:247], 0, v[244:245]
	v_mov_b32_e32 v242, v56
	v_mov_b32_e32 v243, v57
	v_cndmask_b32_e64 v56, v102, v106, s[40:41]
	v_mov_b32_e32 v60, v1
	v_mov_b32_e32 v61, v1
	v_cndmask_b32_e64 v57, v100, v104, s[40:41]
	v_mov_b32_dpp v60, v56 row_ror:1 row_mask:0xf bank_mask:0xf
	v_cndmask_b32_e64 v56, v103, v107, s[40:41]
	v_cndmask_b32_e64 v59, v101, v105, s[40:41]
	v_mov_b32_e32 v62, v1
	v_mov_b32_dpp v61, v56 row_ror:1 row_mask:0xf bank_mask:0xf
	v_mov_b32_e32 v56, v1
	v_mov_b32_e32 v63, v1
	v_mov_b32_e32 v58, v1
	v_mov_b32_dpp v56, v57 row_ror:1 row_mask:0xf bank_mask:0xf
	v_mov_b32_e32 v57, v1
	v_mov_b32_dpp v62, v102 row_ror:15 row_mask:0xf bank_mask:0xf
	v_mov_b32_dpp v63, v103 row_ror:15 row_mask:0xf bank_mask:0xf
	v_mov_b32_dpp v57, v59 row_ror:1 row_mask:0xf bank_mask:0xf
	v_mov_b32_e32 v59, v1
	v_mov_b32_dpp v58, v100 row_ror:15 row_mask:0xf bank_mask:0xf
	s_nop 0
	v_mov_b32_dpp v59, v101 row_ror:15 row_mask:0xf bank_mask:0xf
	s_mov_b64 s[100:101], s[64:65]
	s_and_saveexec_b64 s[16:17], s[64:65]
	s_cbranch_execz .LBB0_703
	s_waitcnt vmcnt(0)
	v_pk_fma_f32 v[60:61], v[84:85], v[60:61], v[96:97]
	v_pk_fma_f32 v[56:57], v[86:87], v[56:57], v[98:99]
	v_pk_fma_f32 v[60:61], v[88:89], v[102:103], v[60:61]
	v_pk_fma_f32 v[56:57], v[90:91], v[100:101], v[56:57]
	v_pk_fma_f32 v[60:61], v[92:93], v[62:63], v[60:61]
	v_pk_fma_f32 v[56:57], v[94:95], v[58:59], v[56:57]
	v_mul_f32_e32 v62, 0xbfb8aa3b, v60
	v_mul_f32_e32 v63, 0xbfb8aa3b, v61
	v_mul_f32_e32 v58, 0xbfb8aa3b, v56
	v_mul_f32_e32 v59, 0xbfb8aa3b, v57
	v_exp_f32_e32 v62, v62
	v_exp_f32_e32 v63, v63
	v_exp_f32_e32 v58, v58
	v_exp_f32_e32 v59, v59
	v_add_f32_e32 v62, 1.0, v62
	v_add_f32_e32 v63, 1.0, v63
	v_add_f32_e32 v58, 1.0, v58
	v_add_f32_e32 v59, 1.0, v59
	v_rcp_f32_e32 v62, v62
	v_rcp_f32_e32 v63, v63
	v_rcp_f32_e32 v58, v58
	v_rcp_f32_e32 v59, v59
	v_pk_mul_f32 v[60:61], v[60:61], v[62:63]
	s_nop 0
	v_pk_mul_f32 v[52:53], v[52:53], v[60:61]
	v_pk_mul_f32 v[56:57], v[56:57], v[58:59]
	v_cvt_pk_bf16_f32 v52, v52, v53
	v_pk_mul_f32 v[54:55], v[54:55], v[56:57]
	s_nop 0
	v_cvt_pk_bf16_f32 v53, v54, v55
	v_mov_b64_e32 v[54:55], s[24:25]
	v_mad_i64_i32 v[54:55], s[36:37], v149, s0, v[54:55]
	v_lshl_add_u64 v[54:55], v[172:173], 1, v[54:55]
.LBB0_703:
	s_or_b64 exec, exec, s[16:17]
	v_mov_b32_e32 v244, v52
	v_mov_b32_e32 v245, v53
	s_nop 1
	v_permlane16_swap_b32_e32 v242, v244
	v_permlane16_swap_b32_e32 v243, v245
	s_and_b32 s98, s98, 0xffff
	s_and_b32 s99, s99, 0xffff
	s_and_b32 s100, s100, 0xffff0000
	s_and_b32 s101, s101, 0xffff0000
	s_or_b64 s[98:99], s[98:99], s[100:101]
	s_mov_b64 s[100:101], exec
	s_mov_b64 exec, s[98:99]
	global_store_dwordx4 v[246:247], v[242:245], off offset:32
	s_mov_b64 exec, s[100:101]
	s_andn2_b64 vcc, exec, s[66:67]
	s_mov_b64 s[16:17], -1
	s_cbranch_vccnz .LBB0_705
	v_cmp_gt_u32_e32 vcc, s5, v151
	v_add_u32_e32 v52, 16, v151
	s_nop 0
	v_cndmask_b32_e32 v66, 0, v48, vcc
	v_cndmask_b32_e32 v67, 0, v49, vcc
	v_cndmask_b32_e32 v64, 0, v50, vcc
	v_cndmask_b32_e32 v65, 0, v51, vcc
	v_cmp_gt_u32_e32 vcc, s5, v52
	v_add_u32_e32 v52, 32, v151
	s_nop 0
	v_cndmask_b32_e32 v62, 0, v44, vcc
	v_cndmask_b32_e32 v63, 0, v45, vcc
	v_cndmask_b32_e32 v60, 0, v46, vcc
	v_cndmask_b32_e32 v61, 0, v47, vcc
	v_cmp_gt_u32_e32 vcc, s5, v52
	v_add_u32_e32 v52, 48, v151
	s_nop 0
	v_cndmask_b32_e32 v58, 0, v40, vcc
	v_cndmask_b32_e32 v59, 0, v41, vcc
	v_cndmask_b32_e32 v56, 0, v42, vcc
	v_cndmask_b32_e32 v57, 0, v43, vcc
	v_cmp_gt_u32_e32 vcc, s5, v52
	s_nop 1
	v_cndmask_b32_e32 v54, 0, v36, vcc
	v_cndmask_b32_e32 v55, 0, v37, vcc
	v_cndmask_b32_e32 v52, 0, v38, vcc
	v_cndmask_b32_e32 v53, 0, v39, vcc
	s_cbranch_execz .LBB0_706
	s_branch .LBB0_707

; DI unsigned pack2(float a, float b) { f2_t v = {a, b}; return __builtin_bit_cast(unsigned, __builtin_convertvector(v, bf2_t)); }
; DI float exp2_hw(float x) { return __builtin_amdgcn_exp2f(x); }
; DI float dpp_ror1(float v)  { return __builtin_bit_cast(float, __builtin_amdgcn_update_dpp(0, __builtin_bit_cast(int, v), 0x121, 0xf, 0xf, false)); }
; DI float dpp_ror15(float v) { return __builtin_bit_cast(float, __builtin_amdgcn_update_dpp(0, __builtin_bit_cast(int, v), 0x12F, 0xf, 0xf, false)); }
;   DI void operator()(const f32x4 (&acc)[2][2][4][2], const pg8::Unit& u, int wr, int wc, int fr, int fq) const {
;     ...
;         if (tokb >= 0 && tokb + 63 < S) {
; #pragma unroll
;           for (int m = 0; m < 4; ++m) g[m] = acc[ai][0][m][n];
;         } else {
; #pragma unroll
;           for (int m = 0; m < 4; ++m) {
;             const int tok = tokb + 16 * m + fr;
;             const bool ok = (tok >= 0) && (tok < S);
; #pragma unroll
;             for (int e = 0; e < 4; ++e) g[m][e] = ok ? acc[ai][0][m][n][e] : 0.f;
;           }
;         }
; #pragma unroll
;         for (int m = 0; m < 4; ++m) {
;           const int q = 16 * m + fr, tok = tokb + q;
;           f32x4 r;
; #pragma unroll
;           for (int e = 0; e < 4; ++e) {
;             const float srcm = (fr == 15 && m > 0) ? g[m > 0 ? m - 1 : 0][e] : g[m][e];
;             const float srcp = (fr == 0 && m < 3) ? g[m < 3 ? m + 1 : 3][e] : g[m][e];
;             const float gm = dpp_ror1(srcm), gp = dpp_ror15(srcp);
;             const float cv = bb[e] + w0[e] * gm + w1[e] * g[m][e] + w2[e] * gp;
;             r[e] = cv * __builtin_amdgcn_rcpf(1.f + exp2_hw(-LOG2E * cv)) * acc[ai][1][m][n][e];
;           }
;           if (q >= 1 && q <= 62 && tok < S)
;             *(uint2*)(act + (size_t)(b * S + tok) * DFF + col) = make_uint2(pack2(r[0], r[1]), pack2(r[2], r[3]));
;         }
.LBB0_707:
	v_cndmask_b32_e64 v36, v66, v62, s[42:43]
	v_mov_b32_e32 v42, v1
	v_mov_b32_e32 v43, v1
	v_cndmask_b32_e64 v37, v64, v60, s[42:43]
	v_mov_b32_dpp v42, v36 row_ror:15 row_mask:0xf bank_mask:0xf
	v_cndmask_b32_e64 v36, v67, v63, s[42:43]
	v_mov_b32_e32 v38, v1
	v_mov_b32_e32 v40, v1
	v_mov_b32_e32 v41, v1
	v_mov_b32_dpp v43, v36 row_ror:15 row_mask:0xf bank_mask:0xf
	v_mov_b32_e32 v36, v1
	v_mov_b32_dpp v38, v37 row_ror:15 row_mask:0xf bank_mask:0xf
	v_cndmask_b32_e64 v44, v65, v61, s[42:43]
	v_mov_b32_e32 v37, v1
	v_mov_b32_e32 v39, v1
	v_mov_b32_dpp v40, v66 row_ror:1 row_mask:0xf bank_mask:0xf
	v_mov_b32_dpp v41, v67 row_ror:1 row_mask:0xf bank_mask:0xf
	v_mov_b32_dpp v36, v64 row_ror:1 row_mask:0xf bank_mask:0xf
	v_mov_b32_dpp v37, v65 row_ror:1 row_mask:0xf bank_mask:0xf
	v_mov_b32_dpp v39, v44 row_ror:15 row_mask:0xf bank_mask:0xf
	s_mov_b64 s[98:99], s[68:69]
	s_and_saveexec_b64 s[16:17], s[68:69]
	s_cbranch_execz .LBB0_709
	s_waitcnt vmcnt(0)
	v_pk_fma_f32 v[40:41], v[84:85], v[40:41], v[96:97]
	v_pk_fma_f32 v[36:37], v[86:87], v[36:37], v[98:99]
	v_pk_fma_f32 v[40:41], v[88:89], v[66:67], v[40:41]
	v_pk_fma_f32 v[36:37], v[90:91], v[64:65], v[36:37]
	v_pk_fma_f32 v[40:41], v[92:93], v[42:43], v[40:41]
	v_pk_fma_f32 v[36:37], v[94:95], v[38:39], v[36:37]
	v_mul_f32_e32 v42, 0xbfb8aa3b, v40
	v_mul_f32_e32 v43, 0xbfb8aa3b, v41
	v_mul_f32_e32 v38, 0xbfb8aa3b, v36
	v_mul_f32_e32 v39, 0xbfb8aa3b, v37
	v_exp_f32_e32 v42, v42
	v_exp_f32_e32 v43, v43
	v_exp_f32_e32 v38, v38
	v_exp_f32_e32 v39, v39
	v_add_f32_e32 v42, 1.0, v42
	v_add_f32_e32 v43, 1.0, v43
	v_add_f32_e32 v38, 1.0, v38
	v_add_f32_e32 v39, 1.0, v39
	v_rcp_f32_e32 v42, v42
	v_rcp_f32_e32 v43, v43
	v_rcp_f32_e32 v38, v38
	v_rcp_f32_e32 v39, v39
	v_pk_mul_f32 v[40:41], v[40:41], v[42:43]
	s_nop 0
	v_pk_mul_f32 v[32:33], v[32:33], v[40:41]
	v_pk_mul_f32 v[36:37], v[36:37], v[38:39]
	v_cvt_pk_bf16_f32 v32, v32, v33
	v_pk_mul_f32 v[34:35], v[34:35], v[36:37]
	s_nop 0
	v_cvt_pk_bf16_f32 v33, v34, v35
	v_mov_b64_e32 v[34:35], s[24:25]
	v_mad_i64_i32 v[34:35], s[36:37], v150, s0, v[34:35]
	v_lshl_add_u64 v[34:35], v[172:173], 1, v[34:35]
.LBB0_709:
	s_or_b64 exec, exec, s[16:17]
	v_mov_b64_e32 v[246:247], s[24:25]
	v_mad_i64_i32 v[246:247], s[100:101], v150, s0, v[246:247]
	v_lshl_add_u64 v[246:247], v[172:173], 1, v[246:247]
	v_bfe_u32 v244, v227, 4, 1
	v_mul_u32_u24_e32 v244, 0x15ff8, v244
	v_mov_b32_e32 v245, 0
	v_lshl_add_u64 v[246:247], v[246:247], 0, v[244:245]
	v_mov_b32_e32 v242, v32
	v_mov_b32_e32 v243, v33
	v_cndmask_b32_e64 v32, v62, v66, s[40:41]
	v_cndmask_b32_e64 v33, v62, v58, s[42:43]
	v_mov_b32_e32 v36, v1
	v_mov_b32_e32 v38, v1
	v_mov_b32_e32 v37, v1
	v_mov_b32_dpp v36, v32 row_ror:1 row_mask:0xf bank_mask:0xf
	v_mov_b32_dpp v38, v33 row_ror:15 row_mask:0xf bank_mask:0xf
	v_cndmask_b32_e64 v32, v63, v67, s[40:41]
	v_cndmask_b32_e64 v33, v63, v59, s[42:43]
	v_mov_b32_e32 v39, v1
	v_mov_b32_dpp v37, v32 row_ror:1 row_mask:0xf bank_mask:0xf
	v_cndmask_b32_e64 v35, v60, v56, s[42:43]
	v_mov_b32_dpp v39, v33 row_ror:15 row_mask:0xf bank_mask:0xf
	v_cndmask_b32_e64 v33, v60, v64, s[40:41]
	v_mov_b32_e32 v32, v1
	v_mov_b32_e32 v34, v1
	v_cndmask_b32_e64 v40, v61, v57, s[42:43]
	v_mov_b32_dpp v32, v33 row_ror:1 row_mask:0xf bank_mask:0xf
	v_mov_b32_dpp v34, v35 row_ror:15 row_mask:0xf bank_mask:0xf
	v_cndmask_b32_e64 v35, v61, v65, s[40:41]
	v_mov_b32_e32 v33, v1
	s_nop 1
	v_mov_b32_dpp v33, v35 row_ror:1 row_mask:0xf bank_mask:0xf
	v_mov_b32_e32 v35, v1
	s_nop 1
	v_mov_b32_dpp v35, v40 row_ror:15 row_mask:0xf bank_mask:0xf
	s_mov_b64 s[100:101], s[54:55]
	s_and_saveexec_b64 s[16:17], s[54:55]
	s_cbranch_execz .LBB0_711
	s_waitcnt vmcnt(0)
	v_pk_fma_f32 v[36:37], v[84:85], v[36:37], v[96:97]
	v_pk_fma_f32 v[32:33], v[86:87], v[32:33], v[98:99]
	v_pk_fma_f32 v[36:37], v[88:89], v[62:63], v[36:37]
	v_pk_fma_f32 v[32:33], v[90:91], v[60:61], v[32:33]
	v_pk_fma_f32 v[36:37], v[92:93], v[38:39], v[36:37]
	v_pk_fma_f32 v[32:33], v[94:95], v[34:35], v[32:33]
	v_mul_f32_e32 v38, 0xbfb8aa3b, v36
	v_mul_f32_e32 v39, 0xbfb8aa3b, v37
	v_mul_f32_e32 v34, 0xbfb8aa3b, v32
	v_mul_f32_e32 v35, 0xbfb8aa3b, v33
	v_exp_f32_e32 v38, v38
	v_exp_f32_e32 v39, v39
	v_exp_f32_e32 v34, v34
	v_exp_f32_e32 v35, v35
	v_add_f32_e32 v38, 1.0, v38
	v_add_f32_e32 v39, 1.0, v39
	v_add_f32_e32 v34, 1.0, v34
	v_add_f32_e32 v35, 1.0, v35
	v_rcp_f32_e32 v38, v38
	v_rcp_f32_e32 v39, v39
	v_rcp_f32_e32 v34, v34
	v_rcp_f32_e32 v35, v35
	v_pk_mul_f32 v[36:37], v[36:37], v[38:39]
	s_nop 0
	v_pk_mul_f32 v[10:11], v[10:11], v[36:37]
	v_pk_mul_f32 v[32:33], v[32:33], v[34:35]
	v_cvt_pk_bf16_f32 v10, v10, v11
	v_pk_mul_f32 v[12:13], v[12:13], v[32:33]
	s_nop 0
	v_cvt_pk_bf16_f32 v11, v12, v13
	v_mov_b64_e32 v[12:13], s[24:25]
	v_mad_i64_i32 v[12:13], s[36:37], v144, s0, v[12:13]
	v_lshl_add_u64 v[12:13], v[172:173], 1, v[12:13]
; DI unsigned pack2(float a, float b) { f2_t v = {a, b}; return __builtin_bit_cast(unsigned, __builtin_convertvector(v, bf2_t)); }
; DI float exp2_hw(float x) { return __builtin_amdgcn_exp2f(x); }
; DI float dpp_ror1(float v)  { return __builtin_bit_cast(float, __builtin_amdgcn_update_dpp(0, __builtin_bit_cast(int, v), 0x121, 0xf, 0xf, false)); }
; DI float dpp_ror15(float v) { return __builtin_bit_cast(float, __builtin_amdgcn_update_dpp(0, __builtin_bit_cast(int, v), 0x12F, 0xf, 0xf, false)); }
;   DI void operator()(const f32x4 (&acc)[2][2][4][2], const pg8::Unit& u, int wr, int wc, int fr, int fq) const {
;     ...
; #pragma unroll
;         for (int m = 0; m < 4; ++m) {
;           const int q = 16 * m + fr, tok = tokb + q;
;           f32x4 r;
; #pragma unroll
;           for (int e = 0; e < 4; ++e) {
;             const float srcm = (fr == 15 && m > 0) ? g[m > 0 ? m - 1 : 0][e] : g[m][e];
;             const float srcp = (fr == 0 && m < 3) ? g[m < 3 ? m + 1 : 3][e] : g[m][e];
;             const float gm = dpp_ror1(srcm), gp = dpp_ror15(srcp);
;             const float cv = bb[e] + w0[e] * gm + w1[e] * g[m][e] + w2[e] * gp;
;             r[e] = cv * __builtin_amdgcn_rcpf(1.f + exp2_hw(-LOG2E * cv)) * acc[ai][1][m][n][e];
;           }
;           if (q >= 1 && q <= 62 && tok < S)
;             *(uint2*)(act + (size_t)(b * S + tok) * DFF + col) = make_uint2(pack2(r[0], r[1]), pack2(r[2], r[3]));
;         }
.LBB0_711:
	s_or_b64 exec, exec, s[16:17]
	v_mov_b32_e32 v244, v10
	v_mov_b32_e32 v245, v11
	s_nop 1
	v_permlane16_swap_b32_e32 v242, v244
	v_permlane16_swap_b32_e32 v243, v245
	s_and_b32 s98, s98, 0xffff
	s_and_b32 s99, s99, 0xffff
	s_and_b32 s100, s100, 0xffff0000
	s_and_b32 s101, s101, 0xffff0000
	s_or_b64 s[98:99], s[98:99], s[100:101]
	s_mov_b64 s[100:101], exec
	s_mov_b64 exec, s[98:99]
	global_store_dwordx4 v[246:247], v[242:245], off offset:32
	s_mov_b64 exec, s[100:101]
	v_cndmask_b32_e64 v10, v58, v62, s[40:41]
	v_cndmask_b32_e64 v11, v58, v54, s[42:43]
	v_mov_b32_e32 v32, v1
	v_mov_b32_e32 v34, v1
	v_mov_b32_e32 v33, v1
	v_mov_b32_dpp v32, v10 row_ror:1 row_mask:0xf bank_mask:0xf
	v_mov_b32_dpp v34, v11 row_ror:15 row_mask:0xf bank_mask:0xf
	v_cndmask_b32_e64 v10, v59, v63, s[40:41]
	v_cndmask_b32_e64 v11, v59, v55, s[42:43]
	v_mov_b32_e32 v35, v1
	v_mov_b32_dpp v33, v10 row_ror:1 row_mask:0xf bank_mask:0xf
	v_cndmask_b32_e64 v13, v56, v52, s[42:43]
	v_mov_b32_dpp v35, v11 row_ror:15 row_mask:0xf bank_mask:0xf
	v_cndmask_b32_e64 v11, v56, v60, s[40:41]
	v_mov_b32_e32 v10, v1
	v_mov_b32_e32 v12, v1
	v_cndmask_b32_e64 v36, v57, v53, s[42:43]
	v_mov_b32_dpp v10, v11 row_ror:1 row_mask:0xf bank_mask:0xf
	v_mov_b32_dpp v12, v13 row_ror:15 row_mask:0xf bank_mask:0xf
	v_cndmask_b32_e64 v13, v57, v61, s[40:41]
	v_mov_b32_e32 v11, v1
	s_nop 1
	v_mov_b32_dpp v11, v13 row_ror:1 row_mask:0xf bank_mask:0xf
	v_mov_b32_e32 v13, v1
	s_nop 1
	v_mov_b32_dpp v13, v36 row_ror:15 row_mask:0xf bank_mask:0xf
	s_mov_b64 s[98:99], s[56:57]
	s_and_saveexec_b64 s[16:17], s[56:57]
	s_cbranch_execz .LBB0_713
	s_waitcnt vmcnt(0)
	v_pk_fma_f32 v[32:33], v[84:85], v[32:33], v[96:97]
	v_pk_fma_f32 v[10:11], v[86:87], v[10:11], v[98:99]
	v_pk_fma_f32 v[32:33], v[88:89], v[58:59], v[32:33]
	v_pk_fma_f32 v[10:11], v[90:91], v[56:57], v[10:11]
	v_pk_fma_f32 v[32:33], v[92:93], v[34:35], v[32:33]
	v_pk_fma_f32 v[10:11], v[94:95], v[12:13], v[10:11]
	v_mul_f32_e32 v34, 0xbfb8aa3b, v32
	v_mul_f32_e32 v35, 0xbfb8aa3b, v33
	v_mul_f32_e32 v12, 0xbfb8aa3b, v10
	v_mul_f32_e32 v13, 0xbfb8aa3b, v11
	v_exp_f32_e32 v34, v34
	v_exp_f32_e32 v35, v35
	v_exp_f32_e32 v12, v12
	v_exp_f32_e32 v13, v13
	v_add_f32_e32 v34, 1.0, v34
	v_add_f32_e32 v35, 1.0, v35
	v_add_f32_e32 v12, 1.0, v12
	v_add_f32_e32 v13, 1.0, v13
	v_rcp_f32_e32 v34, v34
	v_rcp_f32_e32 v35, v35
	v_rcp_f32_e32 v12, v12
	v_rcp_f32_e32 v13, v13
	v_pk_mul_f32 v[32:33], v[32:33], v[34:35]
	s_nop 0
	v_pk_mul_f32 v[6:7], v[6:7], v[32:33]
	v_pk_mul_f32 v[10:11], v[10:11], v[12:13]
	v_cvt_pk_bf16_f32 v6, v6, v7
	v_pk_mul_f32 v[8:9], v[8:9], v[10:11]
	s_nop 0
	v_cvt_pk_bf16_f32 v7, v8, v9
	v_mov_b64_e32 v[8:9], s[24:25]
	v_mad_i64_i32 v[8:9], s[36:37], v124, s0, v[8:9]
	v_lshl_add_u64 v[8:9], v[172:173], 1, v[8:9]
.LBB0_713:
	s_or_b64 exec, exec, s[16:17]
	v_mov_b64_e32 v[246:247], s[24:25]
	v_mad_i64_i32 v[246:247], s[100:101], v124, s0, v[246:247]
	v_lshl_add_u64 v[246:247], v[172:173], 1, v[246:247]
	v_bfe_u32 v244, v227, 4, 1
	v_mul_u32_u24_e32 v244, 0x15ff8, v244
	v_mov_b32_e32 v245, 0
	v_lshl_add_u64 v[246:247], v[246:247], 0, v[244:245]
	v_mov_b32_e32 v242, v6
	v_mov_b32_e32 v243, v7
	v_cndmask_b32_e64 v6, v54, v58, s[40:41]
	v_mov_b32_e32 v10, v1
	v_mov_b32_e32 v11, v1
	v_cndmask_b32_e64 v7, v52, v56, s[40:41]
	v_mov_b32_dpp v10, v6 row_ror:1 row_mask:0xf bank_mask:0xf
	v_cndmask_b32_e64 v6, v55, v59, s[40:41]
	v_cndmask_b32_e64 v9, v53, v57, s[40:41]
	v_mov_b32_e32 v12, v1
	v_mov_b32_dpp v11, v6 row_ror:1 row_mask:0xf bank_mask:0xf
	v_mov_b32_e32 v6, v1
	v_mov_b32_e32 v13, v1
	v_mov_b32_e32 v8, v1
	v_mov_b32_dpp v6, v7 row_ror:1 row_mask:0xf bank_mask:0xf
	v_mov_b32_e32 v7, v1
	v_mov_b32_dpp v12, v54 row_ror:15 row_mask:0xf bank_mask:0xf
	v_mov_b32_dpp v13, v55 row_ror:15 row_mask:0xf bank_mask:0xf
	v_mov_b32_dpp v7, v9 row_ror:1 row_mask:0xf bank_mask:0xf
	v_mov_b32_e32 v9, v1
	v_mov_b32_dpp v8, v52 row_ror:15 row_mask:0xf bank_mask:0xf
	s_nop 0
	v_mov_b32_dpp v9, v53 row_ror:15 row_mask:0xf bank_mask:0xf
	s_mov_b64 s[100:101], s[72:73]
	s_and_saveexec_b64 s[16:17], s[72:73]
	s_cbranch_execz .LBB0_656
	s_waitcnt vmcnt(0)
	v_pk_fma_f32 v[10:11], v[84:85], v[10:11], v[96:97]
	v_pk_fma_f32 v[6:7], v[86:87], v[6:7], v[98:99]
	v_pk_fma_f32 v[10:11], v[88:89], v[54:55], v[10:11]
	v_pk_fma_f32 v[6:7], v[90:91], v[52:53], v[6:7]
	v_pk_fma_f32 v[10:11], v[92:93], v[12:13], v[10:11]
	v_pk_fma_f32 v[6:7], v[94:95], v[8:9], v[6:7]
	v_mul_f32_e32 v12, 0xbfb8aa3b, v10
	v_mul_f32_e32 v13, 0xbfb8aa3b, v11
	v_mul_f32_e32 v8, 0xbfb8aa3b, v6
	v_mul_f32_e32 v9, 0xbfb8aa3b, v7
	v_exp_f32_e32 v12, v12
	v_exp_f32_e32 v13, v13
	v_exp_f32_e32 v8, v8
	v_exp_f32_e32 v9, v9
	v_add_f32_e32 v12, 1.0, v12
	v_add_f32_e32 v13, 1.0, v13
	v_add_f32_e32 v8, 1.0, v8
	v_add_f32_e32 v9, 1.0, v9
	v_rcp_f32_e32 v12, v12
	v_rcp_f32_e32 v13, v13
	v_rcp_f32_e32 v8, v8
	v_rcp_f32_e32 v9, v9
	v_pk_mul_f32 v[10:11], v[10:11], v[12:13]
	s_nop 0
	v_pk_mul_f32 v[2:3], v[2:3], v[10:11]
	v_pk_mul_f32 v[6:7], v[6:7], v[8:9]
	v_cvt_pk_bf16_f32 v2, v2, v3
	v_pk_mul_f32 v[4:5], v[4:5], v[6:7]
	s_nop 0
	v_cvt_pk_bf16_f32 v3, v4, v5
	v_mov_b64_e32 v[4:5], s[24:25]
	v_mad_i64_i32 v[4:5], s[36:37], v120, s0, v[4:5]
	v_lshl_add_u64 v[4:5], v[172:173], 1, v[4:5]
	s_branch .LBB0_656
.LBB0_715:
	v_lshlrev_b32_e32 v242, 2, v232
	v_lshlrev_b32_e32 v243, 2, v230
	v_xor_b32_e32 v244, 8, v227
	v_lshlrev_b32_e32 v244, 2, v244
	v_lshlrev_b32_e32 v245, 2, v233
	v_xor_b32_e32 v246, 2, v227
	v_lshlrev_b32_e32 v246, 2, v246
	v_xor_b32_e32 v247, 1, v227
	v_lshlrev_b32_e32 v247, 2, v247
	s_waitcnt vmcnt(0)
	v_readlane_b32 s82, v255, 8
	v_readlane_b32 s38, v255, 16
	s_cmpk_gt_u32 s12, 0xff
	v_readlane_b32 s83, v255, 9
	v_readlane_b32 s39, v255, 17
	s_cbranch_scc1 .LBB0_717
	s_barrier
